# code placement: every 32-MFMA block start 8-byte aligned (padding placed before the pre-barrier wait)
# speedup vs baseline: 1.0032x; 1.0032x over previous
; #define PG8_STAGE(bufoff, gbase, voff) do { _Pragma("unroll") for (int _i = 0; _i < 2; ++_i) \
;         __builtin_amdgcn_global_load_lds((const unsigned*)((const char*)(gbase) + (voff)[_i]), (PG8_LAS unsigned*)(lds + (bufoff) + ldsw + _i * 8192), 16, 0, 0); } while (0)
; #define PG8_LDA(dst, b, h) do { _Pragma("unroll") for (int m = 0; m < 4; ++m) _Pragma("unroll") for (int k = 0; k < 2; ++k) dst[m][k] = *(const PG8_LAS bf16x8*)(lds + PG8_SA(b, h) + aoff + m * 2048 + k * 1024); } while (0)
; #define PG8_LDB(dst, b, h) do { _Pragma("unroll") for (int n = 0; n < 2; ++n) _Pragma("unroll") for (int k = 0; k < 2; ++k) dst[n][k] = *(const PG8_LAS bf16x8*)(lds + PG8_SB(b, h) + boff + n * 2048 + k * 1024); } while (0)
; #define PG8_WAIT_V(n) asm volatile("s_waitcnt vmcnt(" #n ")" ::: "memory")
; #define PG8_WAIT_L(n) asm volatile("s_waitcnt lgkmcnt(" #n ")" ::: "memory")
; #define PG8_BAR __builtin_amdgcn_s_barrier()
; #define PG8_SCHED __builtin_amdgcn_sched_barrier(0)
; template <class Epi, class Sched, bool ALIGN_EPI = false, bool SP2 = false>
; __device__ __forceinline__ void gemm_phase(PG8_LAS unsigned char* lds, const Gemm g, const Sched& S, const Epi& E) {
;     ...
;         const bool has_next = S.next(ui + 1, nxt);
;         const char* nA = has_next ? (const char*)g.A + (size_t)nxt.pm * tstep : cA; const char* nB = has_next ? (const char*)g.Bt + (size_t)nxt.pn * tstep : cB;
;         for (int t = 0; t < nt; t += 2) {
;             const bool last = (t == nt - 2);
;             const char* a1 = cA + (size_t)(t + 1) * kstepA;
;             const char* a2 = last ? nA : cA + (size_t)(t + 2) * kstepA; const char* b2 = last ? nB : cB + (size_t)(t + 2) * kstep;
;             const char* a3 = a2 + kstepA; const char* b3 = b2 + kstep;
;             if (last && has_next) S.a_ready(nxt);
;             if constexpr (SP2) {
;             PG8_LDB(B0, 0, 0); PG8_LDB(B1, 0, 1); PG8_SCHED; PG8_LDA(At, 0, 0); PG8_STAGE(PG8_SA(1, 1), a1 + hstep, voffA);
;             PG8_WAIT_V(8); PG8_WAIT_L(0); PG8_BAR; PG8_MMA(0, 0, At, B0); PG8_MMA(0, 1, At, B1); PG8_BAR; PG8_SCHED;
;             PG8_LDA(At, 0, 1); PG8_STAGE(PG8_SB(0, 0), b2, voffB); PG8_STAGE(PG8_SB(0, 1), b2 + hstep, voffB); PG8_STAGE(PG8_SA(0, 0), a2, voffA);
;             PG8_WAIT_V(8); PG8_WAIT_L(0); PG8_BAR; PG8_MMA(1, 0, At, B0); PG8_MMA(1, 1, At, B1); PG8_BAR; PG8_SCHED;
.LBB0_237:
	s_ashr_i32 s11, s10, 31
	s_lshl_b64 s[2:3], s[10:11], 19
	s_add_u32 s12, s52, s2
	s_addc_u32 s13, s53, s3
	s_and_b64 s[2:3], s[40:41], exec
	s_cselect_b32 s11, s13, s25
	s_cselect_b32 s67, s12, s24
	s_ashr_i32 s9, s8, 31
	s_lshl_b64 s[2:3], s[8:9], 19
	s_add_u32 s44, s54, s2
	s_addc_u32 s45, s55, s3
	s_and_b64 s[2:3], s[40:41], exec
	s_cselect_b32 s9, s45, s27
	s_cselect_b32 s68, s44, s26
	s_add_u32 s69, s26, 0x100
	s_addc_u32 s70, s27, 0
	s_mov_b32 s71, -2
	s_add_u32 s2, s24, 0x8000
	s_addc_u32 s3, s25, 0
	s_cmp_eq_u32 s71, 12
	s_cselect_b32 s46, s67, s2
	s_cselect_b32 s47, s11, s3
	s_cselect_b32 s42, s68, s69
	s_cselect_b32 s43, s9, s70
	s_add_u32 s26, s46, 0x4000
	s_addc_u32 s27, s47, 0
	v_add_u32_e32 v148, s76, v150
	s_add_i32 s72, 0, 0x14000
	ds_read_b128 v[144:147], v148
	ds_read_b128 v[160:163], v148 offset:1024
	ds_read_b128 v[164:167], v148 offset:2048
	ds_read_b128 v[168:171], v148 offset:3072
	v_add_u32_e32 v148, s72, v150
	ds_read_b128 v[172:175], v148
	ds_read_b128 v[176:179], v148 offset:1024
	ds_read_b128 v[180:183], v148 offset:2048
	ds_read_b128 v[184:187], v148 offset:3072
	v_lshl_add_u64 v[148:149], s[24:25], 0, v[142:143]
	s_add_i32 m0, s23, 0xc000
	ds_read_b128 v[188:191], v152
	ds_read_b128 v[206:209], v152 offset:1024
	ds_read_b128 v[210:213], v152 offset:2048
	ds_read_b128 v[214:217], v152 offset:3072
	ds_read_b128 v[218:221], v152 offset:4096
	ds_read_b128 v[222:225], v152 offset:5120
	ds_read_b128 v[226:229], v152 offset:6144
	ds_read_b128 v[230:233], v152 offset:7168
	global_load_lds_dwordx4 v[148:149], off
	v_lshl_add_u64 v[148:149], s[24:25], 0, v[140:141]
	s_add_i32 m0, s23, 0xe000
	s_nop 0
	global_load_lds_dwordx4 v[148:149], off
	s_waitcnt vmcnt(8)
	.p2align 3
	s_waitcnt lgkmcnt(0)
	s_barrier
	v_mfma_f32_16x16x32_bf16 v[126:129], v[144:147], v[188:191], 0
	v_mfma_f32_16x16x32_bf16 v[126:129], v[160:163], v[206:209], v[126:129]
	v_mfma_f32_16x16x32_bf16 v[122:125], v[168:171], v[206:209], 0
	v_mfma_f32_16x16x32_bf16 v[122:125], v[164:167], v[188:191], v[122:125]
	v_mfma_f32_16x16x32_bf16 v[106:109], v[164:167], v[210:213], 0
	v_mfma_f32_16x16x32_bf16 v[106:109], v[168:171], v[214:217], v[106:109]
	v_mfma_f32_16x16x32_bf16 v[110:113], v[160:163], v[214:217], 0
	v_mfma_f32_16x16x32_bf16 v[110:113], v[144:147], v[210:213], v[110:113]
	v_mfma_f32_16x16x32_bf16 v[94:97], v[144:147], v[218:221], 0
	v_mfma_f32_16x16x32_bf16 v[94:97], v[160:163], v[222:225], v[94:97]
	v_mfma_f32_16x16x32_bf16 v[90:93], v[168:171], v[222:225], 0
	v_mfma_f32_16x16x32_bf16 v[90:93], v[164:167], v[218:221], v[90:93]
	v_mfma_f32_16x16x32_bf16 v[74:77], v[164:167], v[226:229], 0
	v_mfma_f32_16x16x32_bf16 v[74:77], v[168:171], v[230:233], v[74:77]
	v_mfma_f32_16x16x32_bf16 v[78:81], v[160:163], v[230:233], 0
	v_mfma_f32_16x16x32_bf16 v[78:81], v[144:147], v[226:229], v[78:81]
	v_mfma_f32_16x16x32_bf16 v[118:121], v[172:175], v[188:191], 0
	v_mfma_f32_16x16x32_bf16 v[118:121], v[176:179], v[206:209], v[118:121]
	v_mfma_f32_16x16x32_bf16 v[114:117], v[184:187], v[206:209], 0
	v_mfma_f32_16x16x32_bf16 v[114:117], v[180:183], v[188:191], v[114:117]
	v_mfma_f32_16x16x32_bf16 v[98:101], v[180:183], v[210:213], 0
	v_mfma_f32_16x16x32_bf16 v[98:101], v[184:187], v[214:217], v[98:101]
	v_mfma_f32_16x16x32_bf16 v[102:105], v[176:179], v[214:217], 0
	v_mfma_f32_16x16x32_bf16 v[102:105], v[172:175], v[210:213], v[102:105]
	v_mfma_f32_16x16x32_bf16 v[86:89], v[172:175], v[218:221], 0
	v_mfma_f32_16x16x32_bf16 v[86:89], v[176:179], v[222:225], v[86:89]
	v_mfma_f32_16x16x32_bf16 v[82:85], v[184:187], v[222:225], 0
	v_mfma_f32_16x16x32_bf16 v[82:85], v[180:183], v[218:221], v[82:85]
	v_mfma_f32_16x16x32_bf16 v[66:69], v[180:183], v[226:229], 0
	v_mfma_f32_16x16x32_bf16 v[66:69], v[184:187], v[230:233], v[66:69]
	v_mfma_f32_16x16x32_bf16 v[70:73], v[176:179], v[230:233], 0
	v_mfma_f32_16x16x32_bf16 v[70:73], v[172:175], v[226:229], v[70:73]
	s_barrier
	s_add_i32 s24, s76, s51
	v_lshl_add_u64 v[148:149], s[42:43], 0, v[132:133]
	s_mov_b32 m0, s24
	ds_read_b128 v[188:191], v152 offset:16384
	ds_read_b128 v[206:209], v152 offset:17408
	ds_read_b128 v[210:213], v152 offset:18432
	ds_read_b128 v[214:217], v152 offset:19456
	ds_read_b128 v[218:221], v152 offset:20480
	ds_read_b128 v[222:225], v152 offset:21504
	ds_read_b128 v[226:229], v152 offset:22528
	ds_read_b128 v[230:233], v152 offset:23552
	global_load_lds_dwordx4 v[148:149], off
	s_add_i32 m0, s24, 0x2000
	s_add_u32 s24, s42, 0x40000
	v_lshl_add_u64 v[234:235], s[42:43], 0, v[136:137]
	s_addc_u32 s25, s43, 0
	s_add_i32 s72, s72, s51
	global_load_lds_dwordx4 v[234:235], off
	v_lshl_add_u64 v[236:237], s[24:25], 0, v[132:133]
	s_mov_b32 m0, s72
	s_nop 0
	global_load_lds_dwordx4 v[236:237], off
	v_lshl_add_u64 v[236:237], s[24:25], 0, v[136:137]
	s_add_i32 m0, s72, 0x2000
	s_nop 0
	global_load_lds_dwordx4 v[236:237], off
	v_lshl_add_u64 v[236:237], s[46:47], 0, v[130:131]
	s_mov_b32 m0, s23
	s_nop 0
	global_load_lds_dwordx4 v[236:237], off
	v_lshl_add_u64 v[236:237], s[46:47], 0, v[134:135]
	s_mov_b32 m0, s56
	s_nop 0
	global_load_lds_dwordx4 v[236:237], off
	s_waitcnt vmcnt(8)
	.p2align 3
	s_waitcnt lgkmcnt(0)
	s_barrier
; #define PG8_STAGE(bufoff, gbase, voff) do { _Pragma("unroll") for (int _i = 0; _i < 2; ++_i) \
;         __builtin_amdgcn_global_load_lds((const unsigned*)((const char*)(gbase) + (voff)[_i]), (PG8_LAS unsigned*)(lds + (bufoff) + ldsw + _i * 8192), 16, 0, 0); } while (0)
; #define PG8_LDA(dst, b, h) do { _Pragma("unroll") for (int m = 0; m < 4; ++m) _Pragma("unroll") for (int k = 0; k < 2; ++k) dst[m][k] = *(const PG8_LAS bf16x8*)(lds + PG8_SA(b, h) + aoff + m * 2048 + k * 1024); } while (0)
; #define PG8_LDB(dst, b, h) do { _Pragma("unroll") for (int n = 0; n < 2; ++n) _Pragma("unroll") for (int k = 0; k < 2; ++k) dst[n][k] = *(const PG8_LAS bf16x8*)(lds + PG8_SB(b, h) + boff + n * 2048 + k * 1024); } while (0)
; #define PG8_MMA(ai, bj, At, Bt) do { __builtin_amdgcn_s_setprio(1); _Pragma("unroll") for (int m = 0; m < 4; ++m) _Pragma("unroll") for (int n = 0; n < 2; ++n) _Pragma("unroll") for (int k = 0; k < 2; ++k) \
;         acc[ai][bj][m][n] = __builtin_amdgcn_mfma_f32_16x16x32_bf16(Bt[n][k], At[m][k], acc[ai][bj][m][n], 0, 0, 0); __builtin_amdgcn_s_setprio(0); } while (0)
; #define PG8_WAIT_V(n) asm volatile("s_waitcnt vmcnt(" #n ")" ::: "memory")
; #define PG8_WAIT_L(n) asm volatile("s_waitcnt lgkmcnt(" #n ")" ::: "memory")
; #define PG8_BAR __builtin_amdgcn_s_barrier()
; #define PG8_SCHED __builtin_amdgcn_sched_barrier(0)
; template <class Epi, class Sched, bool ALIGN_EPI = false, bool SP2 = false>
; __device__ __forceinline__ void gemm_phase(PG8_LAS unsigned char* lds, const Gemm g, const Sched& S, const Epi& E) {
;     ...
;             PG8_WAIT_V(8); PG8_WAIT_L(0); PG8_BAR; PG8_MMA(1, 0, At, B0); PG8_MMA(1, 1, At, B1); PG8_BAR; PG8_SCHED;
;             PG8_LDB(B0, 1, 0); PG8_LDB(B1, 1, 1); PG8_SCHED; PG8_LDA(At, 1, 0); PG8_STAGE(PG8_SA(0, 1), a2 + hstep, voffA);
;             PG8_WAIT_V(8); PG8_WAIT_L(0); PG8_BAR; PG8_MMA(0, 0, At, B0); PG8_MMA(0, 1, At, B1); PG8_BAR; PG8_SCHED;
	v_mfma_f32_16x16x32_bf16 v[62:65], v[144:147], v[188:191], 0
	v_mfma_f32_16x16x32_bf16 v[62:65], v[160:163], v[206:209], v[62:65]
	v_mfma_f32_16x16x32_bf16 v[58:61], v[168:171], v[206:209], 0
	v_mfma_f32_16x16x32_bf16 v[58:61], v[164:167], v[188:191], v[58:61]
	v_mfma_f32_16x16x32_bf16 v[42:45], v[164:167], v[210:213], 0
	v_mfma_f32_16x16x32_bf16 v[42:45], v[168:171], v[214:217], v[42:45]
	v_mfma_f32_16x16x32_bf16 v[46:49], v[160:163], v[214:217], 0
	v_mfma_f32_16x16x32_bf16 v[46:49], v[144:147], v[210:213], v[46:49]
	v_mfma_f32_16x16x32_bf16 v[30:33], v[144:147], v[218:221], 0
	v_mfma_f32_16x16x32_bf16 v[30:33], v[160:163], v[222:225], v[30:33]
	v_mfma_f32_16x16x32_bf16 v[26:29], v[168:171], v[222:225], 0
	v_mfma_f32_16x16x32_bf16 v[26:29], v[164:167], v[218:221], v[26:29]
	v_mfma_f32_16x16x32_bf16 v[10:13], v[164:167], v[226:229], 0
	v_mfma_f32_16x16x32_bf16 v[10:13], v[168:171], v[230:233], v[10:13]
	v_mfma_f32_16x16x32_bf16 v[14:17], v[160:163], v[230:233], 0
	v_mfma_f32_16x16x32_bf16 v[14:17], v[144:147], v[226:229], v[14:17]
	v_mfma_f32_16x16x32_bf16 v[54:57], v[172:175], v[188:191], 0
	v_mfma_f32_16x16x32_bf16 v[54:57], v[176:179], v[206:209], v[54:57]
	v_mfma_f32_16x16x32_bf16 v[50:53], v[184:187], v[206:209], 0
	v_mfma_f32_16x16x32_bf16 v[50:53], v[180:183], v[188:191], v[50:53]
	v_mfma_f32_16x16x32_bf16 v[34:37], v[180:183], v[210:213], 0
	v_mfma_f32_16x16x32_bf16 v[34:37], v[184:187], v[214:217], v[34:37]
	v_mfma_f32_16x16x32_bf16 v[38:41], v[176:179], v[214:217], 0
	v_mfma_f32_16x16x32_bf16 v[38:41], v[172:175], v[210:213], v[38:41]
	v_mfma_f32_16x16x32_bf16 v[22:25], v[172:175], v[218:221], 0
	v_mfma_f32_16x16x32_bf16 v[22:25], v[176:179], v[222:225], v[22:25]
	v_mfma_f32_16x16x32_bf16 v[18:21], v[184:187], v[222:225], 0
	v_mfma_f32_16x16x32_bf16 v[18:21], v[180:183], v[218:221], v[18:21]
	v_mfma_f32_16x16x32_bf16 v[2:5], v[180:183], v[226:229], 0
	v_mfma_f32_16x16x32_bf16 v[2:5], v[184:187], v[230:233], v[2:5]
	v_mfma_f32_16x16x32_bf16 v[6:9], v[176:179], v[230:233], 0
	v_mfma_f32_16x16x32_bf16 v[6:9], v[172:175], v[226:229], v[6:9]
	s_barrier
	s_add_i32 s72, 0, 0x18000
	v_add_u32_e32 v153, s72, v150
	s_add_i32 s73, 0, 0x1c000
	ds_read_b128 v[144:147], v153
	ds_read_b128 v[160:163], v153 offset:1024
	ds_read_b128 v[164:167], v153 offset:2048
	ds_read_b128 v[168:171], v153 offset:3072
	v_add_u32_e32 v153, s73, v150
	ds_read_b128 v[172:175], v153
	ds_read_b128 v[176:179], v153 offset:1024
	ds_read_b128 v[180:183], v153 offset:2048
	ds_read_b128 v[184:187], v153 offset:3072
	s_add_u32 s24, s46, 0x40000
	s_addc_u32 s25, s47, 0
	s_mov_b32 m0, s57
	v_lshl_add_u64 v[236:237], s[24:25], 0, v[130:131]
	ds_read_b128 v[188:191], v152 offset:32768
	ds_read_b128 v[206:209], v152 offset:33792
	ds_read_b128 v[210:213], v152 offset:34816
	ds_read_b128 v[214:217], v152 offset:35840
	ds_read_b128 v[218:221], v152 offset:36864
	ds_read_b128 v[222:225], v152 offset:37888
	ds_read_b128 v[226:229], v152 offset:38912
	ds_read_b128 v[230:233], v152 offset:39936
	global_load_lds_dwordx4 v[236:237], off
	v_lshl_add_u64 v[236:237], s[24:25], 0, v[134:135]
	s_mov_b32 m0, s58
	s_nop 0
	global_load_lds_dwordx4 v[236:237], off
	s_waitcnt vmcnt(8)
	.p2align 3
	s_waitcnt lgkmcnt(0)
	s_barrier
	v_mfma_f32_16x16x32_bf16 v[126:129], v[144:147], v[188:191], v[126:129]
	v_mfma_f32_16x16x32_bf16 v[126:129], v[160:163], v[206:209], v[126:129]
	v_mfma_f32_16x16x32_bf16 v[122:125], v[168:171], v[206:209], v[122:125]
	v_mfma_f32_16x16x32_bf16 v[122:125], v[164:167], v[188:191], v[122:125]
	v_mfma_f32_16x16x32_bf16 v[106:109], v[164:167], v[210:213], v[106:109]
	v_mfma_f32_16x16x32_bf16 v[106:109], v[168:171], v[214:217], v[106:109]
	v_mfma_f32_16x16x32_bf16 v[110:113], v[160:163], v[214:217], v[110:113]
	v_mfma_f32_16x16x32_bf16 v[110:113], v[144:147], v[210:213], v[110:113]
	v_mfma_f32_16x16x32_bf16 v[94:97], v[144:147], v[218:221], v[94:97]
	v_mfma_f32_16x16x32_bf16 v[94:97], v[160:163], v[222:225], v[94:97]
	v_mfma_f32_16x16x32_bf16 v[90:93], v[168:171], v[222:225], v[90:93]
	v_mfma_f32_16x16x32_bf16 v[90:93], v[164:167], v[218:221], v[90:93]
	v_mfma_f32_16x16x32_bf16 v[74:77], v[164:167], v[226:229], v[74:77]
	v_mfma_f32_16x16x32_bf16 v[74:77], v[168:171], v[230:233], v[74:77]
	v_mfma_f32_16x16x32_bf16 v[78:81], v[160:163], v[230:233], v[78:81]
	v_mfma_f32_16x16x32_bf16 v[78:81], v[144:147], v[226:229], v[78:81]
	v_mfma_f32_16x16x32_bf16 v[118:121], v[172:175], v[188:191], v[118:121]
	v_mfma_f32_16x16x32_bf16 v[118:121], v[176:179], v[206:209], v[118:121]
	v_mfma_f32_16x16x32_bf16 v[114:117], v[184:187], v[206:209], v[114:117]
	v_mfma_f32_16x16x32_bf16 v[114:117], v[180:183], v[188:191], v[114:117]
	v_mfma_f32_16x16x32_bf16 v[98:101], v[180:183], v[210:213], v[98:101]
	v_mfma_f32_16x16x32_bf16 v[98:101], v[184:187], v[214:217], v[98:101]
	v_mfma_f32_16x16x32_bf16 v[102:105], v[176:179], v[214:217], v[102:105]
	v_mfma_f32_16x16x32_bf16 v[102:105], v[172:175], v[210:213], v[102:105]
	v_mfma_f32_16x16x32_bf16 v[86:89], v[172:175], v[218:221], v[86:89]
	v_mfma_f32_16x16x32_bf16 v[86:89], v[176:179], v[222:225], v[86:89]
	v_mfma_f32_16x16x32_bf16 v[82:85], v[184:187], v[222:225], v[82:85]
	v_mfma_f32_16x16x32_bf16 v[82:85], v[180:183], v[218:221], v[82:85]
	v_mfma_f32_16x16x32_bf16 v[66:69], v[180:183], v[226:229], v[66:69]
	v_mfma_f32_16x16x32_bf16 v[66:69], v[184:187], v[230:233], v[66:69]
	v_mfma_f32_16x16x32_bf16 v[70:73], v[176:179], v[230:233], v[70:73]
	v_mfma_f32_16x16x32_bf16 v[70:73], v[172:175], v[226:229], v[70:73]
	s_barrier
; #define PG8_STAGE(bufoff, gbase, voff) do { _Pragma("unroll") for (int _i = 0; _i < 2; ++_i) \
;         __builtin_amdgcn_global_load_lds((const unsigned*)((const char*)(gbase) + (voff)[_i]), (PG8_LAS unsigned*)(lds + (bufoff) + ldsw + _i * 8192), 16, 0, 0); } while (0)
; #define PG8_LDA(dst, b, h) do { _Pragma("unroll") for (int m = 0; m < 4; ++m) _Pragma("unroll") for (int k = 0; k < 2; ++k) dst[m][k] = *(const PG8_LAS bf16x8*)(lds + PG8_SA(b, h) + aoff + m * 2048 + k * 1024); } while (0)
; #define PG8_LDB(dst, b, h) do { _Pragma("unroll") for (int n = 0; n < 2; ++n) _Pragma("unroll") for (int k = 0; k < 2; ++k) dst[n][k] = *(const PG8_LAS bf16x8*)(lds + PG8_SB(b, h) + boff + n * 2048 + k * 1024); } while (0)
; template <class Epi, class Sched, bool ALIGN_EPI = false, bool SP2 = false>
; __device__ __forceinline__ void gemm_phase(PG8_LAS unsigned char* lds, const Gemm g, const Sched& S, const Epi& E) {
;     ...
;         for (int t = 0; t < nt; t += 2) {
;             const bool last = (t == nt - 2);
;             const char* a1 = cA + (size_t)(t + 1) * kstepA;
;             const char* a2 = last ? nA : cA + (size_t)(t + 2) * kstepA; const char* b2 = last ? nB : cB + (size_t)(t + 2) * kstep;
;             const char* a3 = a2 + kstepA; const char* b3 = b2 + kstep;
;             if (last && has_next) S.a_ready(nxt);
;             if constexpr (SP2) {
;             PG8_LDB(B0, 0, 0); PG8_LDB(B1, 0, 1); PG8_SCHED; PG8_LDA(At, 0, 0); PG8_STAGE(PG8_SA(1, 1), a1 + hstep, voffA);
;             PG8_WAIT_V(8); PG8_WAIT_L(0); PG8_BAR; PG8_MMA(0, 0, At, B0); PG8_MMA(0, 1, At, B1); PG8_BAR; PG8_SCHED;
;             PG8_LDA(At, 0, 1); PG8_STAGE(PG8_SB(0, 0), b2, voffB); PG8_STAGE(PG8_SB(0, 1), b2 + hstep, voffB); PG8_STAGE(PG8_SA(0, 0), a2, voffA);
;             PG8_WAIT_V(8); PG8_WAIT_L(0); PG8_BAR; PG8_MMA(1, 0, At, B0); PG8_MMA(1, 1, At, B1); PG8_BAR; PG8_SCHED;
;             PG8_LDB(B0, 1, 0); PG8_LDB(B1, 1, 1); PG8_SCHED; PG8_LDA(At, 1, 0); PG8_STAGE(PG8_SA(0, 1), a2 + hstep, voffA);
;             PG8_WAIT_V(8); PG8_WAIT_L(0); PG8_BAR; PG8_MMA(0, 0, At, B0); PG8_MMA(0, 1, At, B1); PG8_BAR; PG8_SCHED;
;             PG8_LDA(At, 1, 1); PG8_STAGE(PG8_SB(1, 0), b3, voffB); PG8_STAGE(PG8_SB(1, 1), b3 + hstep, voffB); PG8_STAGE(PG8_SA(1, 0), a3, voffA);
;             PG8_WAIT_V(8); PG8_WAIT_L(0); PG8_BAR; PG8_MMA(1, 0, At, B0); PG8_MMA(1, 1, At, B1); PG8_BAR; PG8_SCHED;
	s_add_i32 s24, s72, s51
	v_lshl_add_u64 v[148:149], v[148:149], 0, s[38:39]
	s_mov_b32 m0, s24
	ds_read_b128 v[188:191], v152 offset:49152
	ds_read_b128 v[206:209], v152 offset:50176
	ds_read_b128 v[210:213], v152 offset:51200
	ds_read_b128 v[214:217], v152 offset:52224
	ds_read_b128 v[218:221], v152 offset:53248
	ds_read_b128 v[222:225], v152 offset:54272
	ds_read_b128 v[226:229], v152 offset:55296
	ds_read_b128 v[230:233], v152 offset:56320
	global_load_lds_dwordx4 v[148:149], off
	s_add_i32 m0, s24, 0x2000
	s_add_u32 s24, s42, 0x40080
	v_lshl_add_u64 v[148:149], v[234:235], 0, s[38:39]
	s_addc_u32 s25, s43, 0
	s_add_i32 s42, s73, s51
	global_load_lds_dwordx4 v[148:149], off
	v_lshl_add_u64 v[148:149], s[24:25], 0, v[132:133]
	s_mov_b32 m0, s42
	s_nop 0
	global_load_lds_dwordx4 v[148:149], off
	v_lshl_add_u64 v[148:149], s[24:25], 0, v[136:137]
	s_add_i32 m0, s42, 0x2000
	s_nop 0
	global_load_lds_dwordx4 v[148:149], off
	v_lshl_add_u64 v[148:149], s[26:27], 0, v[130:131]
	s_mov_b32 m0, s64
	s_nop 0
	global_load_lds_dwordx4 v[148:149], off
	v_lshl_add_u64 v[148:149], s[26:27], 0, v[134:135]
	s_mov_b32 m0, s65
	s_nop 0
	global_load_lds_dwordx4 v[148:149], off
	s_waitcnt vmcnt(8)
	.p2align 3
	s_waitcnt lgkmcnt(0)
	s_barrier
	v_mfma_f32_16x16x32_bf16 v[62:65], v[144:147], v[188:191], v[62:65]
	v_mfma_f32_16x16x32_bf16 v[62:65], v[160:163], v[206:209], v[62:65]
	v_mfma_f32_16x16x32_bf16 v[58:61], v[168:171], v[206:209], v[58:61]
	v_mfma_f32_16x16x32_bf16 v[58:61], v[164:167], v[188:191], v[58:61]
	v_mfma_f32_16x16x32_bf16 v[42:45], v[164:167], v[210:213], v[42:45]
	v_mfma_f32_16x16x32_bf16 v[42:45], v[168:171], v[214:217], v[42:45]
	v_mfma_f32_16x16x32_bf16 v[46:49], v[160:163], v[214:217], v[46:49]
	v_mfma_f32_16x16x32_bf16 v[46:49], v[144:147], v[210:213], v[46:49]
	v_mfma_f32_16x16x32_bf16 v[30:33], v[144:147], v[218:221], v[30:33]
	v_mfma_f32_16x16x32_bf16 v[30:33], v[160:163], v[222:225], v[30:33]
	v_mfma_f32_16x16x32_bf16 v[26:29], v[168:171], v[222:225], v[26:29]
	v_mfma_f32_16x16x32_bf16 v[26:29], v[164:167], v[218:221], v[26:29]
	v_mfma_f32_16x16x32_bf16 v[10:13], v[164:167], v[226:229], v[10:13]
	v_mfma_f32_16x16x32_bf16 v[10:13], v[168:171], v[230:233], v[10:13]
	v_mfma_f32_16x16x32_bf16 v[14:17], v[160:163], v[230:233], v[14:17]
	v_mfma_f32_16x16x32_bf16 v[14:17], v[144:147], v[226:229], v[14:17]
	v_mfma_f32_16x16x32_bf16 v[54:57], v[172:175], v[188:191], v[54:57]
	v_mfma_f32_16x16x32_bf16 v[54:57], v[176:179], v[206:209], v[54:57]
	v_mfma_f32_16x16x32_bf16 v[50:53], v[184:187], v[206:209], v[50:53]
	v_mfma_f32_16x16x32_bf16 v[50:53], v[180:183], v[188:191], v[50:53]
	v_mfma_f32_16x16x32_bf16 v[34:37], v[180:183], v[210:213], v[34:37]
	v_mfma_f32_16x16x32_bf16 v[34:37], v[184:187], v[214:217], v[34:37]
	v_mfma_f32_16x16x32_bf16 v[38:41], v[176:179], v[214:217], v[38:41]
	v_mfma_f32_16x16x32_bf16 v[38:41], v[172:175], v[210:213], v[38:41]
	v_mfma_f32_16x16x32_bf16 v[22:25], v[172:175], v[218:221], v[22:25]
	v_mfma_f32_16x16x32_bf16 v[22:25], v[176:179], v[222:225], v[22:25]
	v_mfma_f32_16x16x32_bf16 v[18:21], v[184:187], v[222:225], v[18:21]
	v_mfma_f32_16x16x32_bf16 v[18:21], v[180:183], v[218:221], v[18:21]
	v_mfma_f32_16x16x32_bf16 v[2:5], v[180:183], v[226:229], v[2:5]
	v_mfma_f32_16x16x32_bf16 v[2:5], v[184:187], v[230:233], v[2:5]
	v_mfma_f32_16x16x32_bf16 v[6:9], v[176:179], v[230:233], v[6:9]
	v_mfma_f32_16x16x32_bf16 v[6:9], v[172:175], v[226:229], v[6:9]
	s_barrier
	s_add_i32 s71, s71, 2
	s_add_u32 s69, s69, 0x100
	s_addc_u32 s70, s70, 0
	s_cmp_gt_u32 s71, 13
	s_mov_b64 s[24:25], s[2:3]
	s_cbranch_scc1 .Lpeel_exit_0
.LBB0_238:
	s_add_u32 s2, s24, 0x8000
	s_addc_u32 s3, s25, 0
	s_cmp_eq_u32 s71, 12
	s_cselect_b32 s46, s67, s2
	s_cselect_b32 s47, s11, s3
	s_cselect_b32 s42, s68, s69
	s_cselect_b32 s43, s9, s70
	s_add_u32 s26, s46, 0x4000
	s_addc_u32 s27, s47, 0
	v_add_u32_e32 v148, s76, v150
	s_add_i32 s72, 0, 0x14000
	ds_read_b128 v[144:147], v148
	ds_read_b128 v[160:163], v148 offset:1024
	ds_read_b128 v[164:167], v148 offset:2048
	ds_read_b128 v[168:171], v148 offset:3072
	v_add_u32_e32 v148, s72, v150
	ds_read_b128 v[172:175], v148
	ds_read_b128 v[176:179], v148 offset:1024
	ds_read_b128 v[180:183], v148 offset:2048
	ds_read_b128 v[184:187], v148 offset:3072
	v_lshl_add_u64 v[148:149], s[24:25], 0, v[142:143]
	s_add_i32 m0, s23, 0xc000
	ds_read_b128 v[188:191], v152
	ds_read_b128 v[206:209], v152 offset:1024
	ds_read_b128 v[210:213], v152 offset:2048
	ds_read_b128 v[214:217], v152 offset:3072
	ds_read_b128 v[218:221], v152 offset:4096
	ds_read_b128 v[222:225], v152 offset:5120
	ds_read_b128 v[226:229], v152 offset:6144
	ds_read_b128 v[230:233], v152 offset:7168
	global_load_lds_dwordx4 v[148:149], off
	v_lshl_add_u64 v[148:149], s[24:25], 0, v[140:141]
	s_add_i32 m0, s23, 0xe000
	s_nop 0
	global_load_lds_dwordx4 v[148:149], off
	s_waitcnt vmcnt(8)
	.p2align 3
	s_waitcnt lgkmcnt(0)
	s_barrier
; #define PG8_STAGE(bufoff, gbase, voff) do { _Pragma("unroll") for (int _i = 0; _i < 2; ++_i) \
;         __builtin_amdgcn_global_load_lds((const unsigned*)((const char*)(gbase) + (voff)[_i]), (PG8_LAS unsigned*)(lds + (bufoff) + ldsw + _i * 8192), 16, 0, 0); } while (0)
; #define PG8_LDA(dst, b, h) do { _Pragma("unroll") for (int m = 0; m < 4; ++m) _Pragma("unroll") for (int k = 0; k < 2; ++k) dst[m][k] = *(const PG8_LAS bf16x8*)(lds + PG8_SA(b, h) + aoff + m * 2048 + k * 1024); } while (0)
; #define PG8_MMA(ai, bj, At, Bt) do { __builtin_amdgcn_s_setprio(1); _Pragma("unroll") for (int m = 0; m < 4; ++m) _Pragma("unroll") for (int n = 0; n < 2; ++n) _Pragma("unroll") for (int k = 0; k < 2; ++k) \
;         acc[ai][bj][m][n] = __builtin_amdgcn_mfma_f32_16x16x32_bf16(Bt[n][k], At[m][k], acc[ai][bj][m][n], 0, 0, 0); __builtin_amdgcn_s_setprio(0); } while (0)
; #define PG8_WAIT_V(n) asm volatile("s_waitcnt vmcnt(" #n ")" ::: "memory")
; #define PG8_WAIT_L(n) asm volatile("s_waitcnt lgkmcnt(" #n ")" ::: "memory")
; #define PG8_BAR __builtin_amdgcn_s_barrier()
; #define PG8_SCHED __builtin_amdgcn_sched_barrier(0)
; template <class Epi, class Sched, bool ALIGN_EPI = false, bool SP2 = false>
; __device__ __forceinline__ void gemm_phase(PG8_LAS unsigned char* lds, const Gemm g, const Sched& S, const Epi& E) {
;     ...
;             PG8_WAIT_V(8); PG8_WAIT_L(0); PG8_BAR; PG8_MMA(0, 0, At, B0); PG8_MMA(0, 1, At, B1); PG8_BAR; PG8_SCHED;
;             PG8_LDA(At, 0, 1); PG8_STAGE(PG8_SB(0, 0), b2, voffB); PG8_STAGE(PG8_SB(0, 1), b2 + hstep, voffB); PG8_STAGE(PG8_SA(0, 0), a2, voffA);
;             PG8_WAIT_V(8); PG8_WAIT_L(0); PG8_BAR; PG8_MMA(1, 0, At, B0); PG8_MMA(1, 1, At, B1); PG8_BAR; PG8_SCHED;
	v_mfma_f32_16x16x32_bf16 v[126:129], v[144:147], v[188:191], v[126:129]
	v_mfma_f32_16x16x32_bf16 v[126:129], v[160:163], v[206:209], v[126:129]
	v_mfma_f32_16x16x32_bf16 v[122:125], v[168:171], v[206:209], v[122:125]
	v_mfma_f32_16x16x32_bf16 v[122:125], v[164:167], v[188:191], v[122:125]
	v_mfma_f32_16x16x32_bf16 v[106:109], v[164:167], v[210:213], v[106:109]
	v_mfma_f32_16x16x32_bf16 v[106:109], v[168:171], v[214:217], v[106:109]
	v_mfma_f32_16x16x32_bf16 v[110:113], v[160:163], v[214:217], v[110:113]
	v_mfma_f32_16x16x32_bf16 v[110:113], v[144:147], v[210:213], v[110:113]
	v_mfma_f32_16x16x32_bf16 v[94:97], v[144:147], v[218:221], v[94:97]
	v_mfma_f32_16x16x32_bf16 v[94:97], v[160:163], v[222:225], v[94:97]
	v_mfma_f32_16x16x32_bf16 v[90:93], v[168:171], v[222:225], v[90:93]
	v_mfma_f32_16x16x32_bf16 v[90:93], v[164:167], v[218:221], v[90:93]
	v_mfma_f32_16x16x32_bf16 v[74:77], v[164:167], v[226:229], v[74:77]
	v_mfma_f32_16x16x32_bf16 v[74:77], v[168:171], v[230:233], v[74:77]
	v_mfma_f32_16x16x32_bf16 v[78:81], v[160:163], v[230:233], v[78:81]
	v_mfma_f32_16x16x32_bf16 v[78:81], v[144:147], v[226:229], v[78:81]
	v_mfma_f32_16x16x32_bf16 v[118:121], v[172:175], v[188:191], v[118:121]
	v_mfma_f32_16x16x32_bf16 v[118:121], v[176:179], v[206:209], v[118:121]
	v_mfma_f32_16x16x32_bf16 v[114:117], v[184:187], v[206:209], v[114:117]
	v_mfma_f32_16x16x32_bf16 v[114:117], v[180:183], v[188:191], v[114:117]
	v_mfma_f32_16x16x32_bf16 v[98:101], v[180:183], v[210:213], v[98:101]
	v_mfma_f32_16x16x32_bf16 v[98:101], v[184:187], v[214:217], v[98:101]
	v_mfma_f32_16x16x32_bf16 v[102:105], v[176:179], v[214:217], v[102:105]
	v_mfma_f32_16x16x32_bf16 v[102:105], v[172:175], v[210:213], v[102:105]
	v_mfma_f32_16x16x32_bf16 v[86:89], v[172:175], v[218:221], v[86:89]
	v_mfma_f32_16x16x32_bf16 v[86:89], v[176:179], v[222:225], v[86:89]
	v_mfma_f32_16x16x32_bf16 v[82:85], v[184:187], v[222:225], v[82:85]
	v_mfma_f32_16x16x32_bf16 v[82:85], v[180:183], v[218:221], v[82:85]
	v_mfma_f32_16x16x32_bf16 v[66:69], v[180:183], v[226:229], v[66:69]
	v_mfma_f32_16x16x32_bf16 v[66:69], v[184:187], v[230:233], v[66:69]
	v_mfma_f32_16x16x32_bf16 v[70:73], v[176:179], v[230:233], v[70:73]
	v_mfma_f32_16x16x32_bf16 v[70:73], v[172:175], v[226:229], v[70:73]
	s_barrier
	s_add_i32 s24, s76, s51
	v_lshl_add_u64 v[148:149], s[42:43], 0, v[132:133]
	s_mov_b32 m0, s24
	ds_read_b128 v[188:191], v152 offset:16384
	ds_read_b128 v[206:209], v152 offset:17408
	ds_read_b128 v[210:213], v152 offset:18432
	ds_read_b128 v[214:217], v152 offset:19456
	ds_read_b128 v[218:221], v152 offset:20480
	ds_read_b128 v[222:225], v152 offset:21504
	ds_read_b128 v[226:229], v152 offset:22528
	ds_read_b128 v[230:233], v152 offset:23552
	global_load_lds_dwordx4 v[148:149], off
	s_add_i32 m0, s24, 0x2000
	s_add_u32 s24, s42, 0x40000
	v_lshl_add_u64 v[234:235], s[42:43], 0, v[136:137]
	s_addc_u32 s25, s43, 0
	s_add_i32 s72, s72, s51
	global_load_lds_dwordx4 v[234:235], off
	v_lshl_add_u64 v[236:237], s[24:25], 0, v[132:133]
	s_mov_b32 m0, s72
	s_nop 0
	global_load_lds_dwordx4 v[236:237], off
	v_lshl_add_u64 v[236:237], s[24:25], 0, v[136:137]
	s_add_i32 m0, s72, 0x2000
	s_nop 0
	global_load_lds_dwordx4 v[236:237], off
	v_lshl_add_u64 v[236:237], s[46:47], 0, v[130:131]
	s_mov_b32 m0, s23
	s_nop 0
	global_load_lds_dwordx4 v[236:237], off
	v_lshl_add_u64 v[236:237], s[46:47], 0, v[134:135]
	s_mov_b32 m0, s56
	s_nop 0
	global_load_lds_dwordx4 v[236:237], off
	s_waitcnt vmcnt(8)
	.p2align 3
	s_waitcnt lgkmcnt(0)
	s_barrier
	v_mfma_f32_16x16x32_bf16 v[62:65], v[144:147], v[188:191], v[62:65]
	v_mfma_f32_16x16x32_bf16 v[62:65], v[160:163], v[206:209], v[62:65]
	v_mfma_f32_16x16x32_bf16 v[58:61], v[168:171], v[206:209], v[58:61]
	v_mfma_f32_16x16x32_bf16 v[58:61], v[164:167], v[188:191], v[58:61]
	v_mfma_f32_16x16x32_bf16 v[42:45], v[164:167], v[210:213], v[42:45]
	v_mfma_f32_16x16x32_bf16 v[42:45], v[168:171], v[214:217], v[42:45]
	v_mfma_f32_16x16x32_bf16 v[46:49], v[160:163], v[214:217], v[46:49]
	v_mfma_f32_16x16x32_bf16 v[46:49], v[144:147], v[210:213], v[46:49]
	v_mfma_f32_16x16x32_bf16 v[30:33], v[144:147], v[218:221], v[30:33]
	v_mfma_f32_16x16x32_bf16 v[30:33], v[160:163], v[222:225], v[30:33]
	v_mfma_f32_16x16x32_bf16 v[26:29], v[168:171], v[222:225], v[26:29]
	v_mfma_f32_16x16x32_bf16 v[26:29], v[164:167], v[218:221], v[26:29]
	v_mfma_f32_16x16x32_bf16 v[10:13], v[164:167], v[226:229], v[10:13]
	v_mfma_f32_16x16x32_bf16 v[10:13], v[168:171], v[230:233], v[10:13]
	v_mfma_f32_16x16x32_bf16 v[14:17], v[160:163], v[230:233], v[14:17]
	v_mfma_f32_16x16x32_bf16 v[14:17], v[144:147], v[226:229], v[14:17]
	v_mfma_f32_16x16x32_bf16 v[54:57], v[172:175], v[188:191], v[54:57]
	v_mfma_f32_16x16x32_bf16 v[54:57], v[176:179], v[206:209], v[54:57]
	v_mfma_f32_16x16x32_bf16 v[50:53], v[184:187], v[206:209], v[50:53]
	v_mfma_f32_16x16x32_bf16 v[50:53], v[180:183], v[188:191], v[50:53]
	v_mfma_f32_16x16x32_bf16 v[34:37], v[180:183], v[210:213], v[34:37]
	v_mfma_f32_16x16x32_bf16 v[34:37], v[184:187], v[214:217], v[34:37]
	v_mfma_f32_16x16x32_bf16 v[38:41], v[176:179], v[214:217], v[38:41]
	v_mfma_f32_16x16x32_bf16 v[38:41], v[172:175], v[210:213], v[38:41]
	v_mfma_f32_16x16x32_bf16 v[22:25], v[172:175], v[218:221], v[22:25]
	v_mfma_f32_16x16x32_bf16 v[22:25], v[176:179], v[222:225], v[22:25]
	v_mfma_f32_16x16x32_bf16 v[18:21], v[184:187], v[222:225], v[18:21]
	v_mfma_f32_16x16x32_bf16 v[18:21], v[180:183], v[218:221], v[18:21]
	v_mfma_f32_16x16x32_bf16 v[2:5], v[180:183], v[226:229], v[2:5]
	v_mfma_f32_16x16x32_bf16 v[2:5], v[184:187], v[230:233], v[2:5]
	v_mfma_f32_16x16x32_bf16 v[6:9], v[176:179], v[230:233], v[6:9]
	v_mfma_f32_16x16x32_bf16 v[6:9], v[172:175], v[226:229], v[6:9]
	s_barrier
; #define PG8_STAGE(bufoff, gbase, voff) do { _Pragma("unroll") for (int _i = 0; _i < 2; ++_i) \
;         __builtin_amdgcn_global_load_lds((const unsigned*)((const char*)(gbase) + (voff)[_i]), (PG8_LAS unsigned*)(lds + (bufoff) + ldsw + _i * 8192), 16, 0, 0); } while (0)
; #define PG8_LDA(dst, b, h) do { _Pragma("unroll") for (int m = 0; m < 4; ++m) _Pragma("unroll") for (int k = 0; k < 2; ++k) dst[m][k] = *(const PG8_LAS bf16x8*)(lds + PG8_SA(b, h) + aoff + m * 2048 + k * 1024); } while (0)
; #define PG8_LDB(dst, b, h) do { _Pragma("unroll") for (int n = 0; n < 2; ++n) _Pragma("unroll") for (int k = 0; k < 2; ++k) dst[n][k] = *(const PG8_LAS bf16x8*)(lds + PG8_SB(b, h) + boff + n * 2048 + k * 1024); } while (0)
; #define PG8_MMA(ai, bj, At, Bt) do { __builtin_amdgcn_s_setprio(1); _Pragma("unroll") for (int m = 0; m < 4; ++m) _Pragma("unroll") for (int n = 0; n < 2; ++n) _Pragma("unroll") for (int k = 0; k < 2; ++k) \
;         acc[ai][bj][m][n] = __builtin_amdgcn_mfma_f32_16x16x32_bf16(Bt[n][k], At[m][k], acc[ai][bj][m][n], 0, 0, 0); __builtin_amdgcn_s_setprio(0); } while (0)
; #define PG8_WAIT_V(n) asm volatile("s_waitcnt vmcnt(" #n ")" ::: "memory")
; #define PG8_WAIT_L(n) asm volatile("s_waitcnt lgkmcnt(" #n ")" ::: "memory")
; #define PG8_BAR __builtin_amdgcn_s_barrier()
; #define PG8_SCHED __builtin_amdgcn_sched_barrier(0)
; template <class Epi, class Sched, bool ALIGN_EPI = false, bool SP2 = false>
; __device__ __forceinline__ void gemm_phase(PG8_LAS unsigned char* lds, const Gemm g, const Sched& S, const Epi& E) {
;     ...
;             PG8_LDB(B0, 1, 0); PG8_LDB(B1, 1, 1); PG8_SCHED; PG8_LDA(At, 1, 0); PG8_STAGE(PG8_SA(0, 1), a2 + hstep, voffA);
;             PG8_WAIT_V(8); PG8_WAIT_L(0); PG8_BAR; PG8_MMA(0, 0, At, B0); PG8_MMA(0, 1, At, B1); PG8_BAR; PG8_SCHED;
;             PG8_LDA(At, 1, 1); PG8_STAGE(PG8_SB(1, 0), b3, voffB); PG8_STAGE(PG8_SB(1, 1), b3 + hstep, voffB); PG8_STAGE(PG8_SA(1, 0), a3, voffA);
;             PG8_WAIT_V(8); PG8_WAIT_L(0); PG8_BAR; PG8_MMA(1, 0, At, B0); PG8_MMA(1, 1, At, B1); PG8_BAR; PG8_SCHED;
	s_add_i32 s72, 0, 0x18000
	v_add_u32_e32 v153, s72, v150
	s_add_i32 s73, 0, 0x1c000
	ds_read_b128 v[144:147], v153
	ds_read_b128 v[160:163], v153 offset:1024
	ds_read_b128 v[164:167], v153 offset:2048
	ds_read_b128 v[168:171], v153 offset:3072
	v_add_u32_e32 v153, s73, v150
	ds_read_b128 v[172:175], v153
	ds_read_b128 v[176:179], v153 offset:1024
	ds_read_b128 v[180:183], v153 offset:2048
	ds_read_b128 v[184:187], v153 offset:3072
	s_add_u32 s24, s46, 0x40000
	s_addc_u32 s25, s47, 0
	s_mov_b32 m0, s57
	v_lshl_add_u64 v[236:237], s[24:25], 0, v[130:131]
	ds_read_b128 v[188:191], v152 offset:32768
	ds_read_b128 v[206:209], v152 offset:33792
	ds_read_b128 v[210:213], v152 offset:34816
	ds_read_b128 v[214:217], v152 offset:35840
	ds_read_b128 v[218:221], v152 offset:36864
	ds_read_b128 v[222:225], v152 offset:37888
	ds_read_b128 v[226:229], v152 offset:38912
	ds_read_b128 v[230:233], v152 offset:39936
	global_load_lds_dwordx4 v[236:237], off
	v_lshl_add_u64 v[236:237], s[24:25], 0, v[134:135]
	s_mov_b32 m0, s58
	s_nop 0
	global_load_lds_dwordx4 v[236:237], off
	s_waitcnt vmcnt(8)
	.p2align 3
	s_waitcnt lgkmcnt(0)
	s_barrier
	v_mfma_f32_16x16x32_bf16 v[126:129], v[144:147], v[188:191], v[126:129]
	v_mfma_f32_16x16x32_bf16 v[126:129], v[160:163], v[206:209], v[126:129]
	v_mfma_f32_16x16x32_bf16 v[122:125], v[168:171], v[206:209], v[122:125]
	v_mfma_f32_16x16x32_bf16 v[122:125], v[164:167], v[188:191], v[122:125]
	v_mfma_f32_16x16x32_bf16 v[106:109], v[164:167], v[210:213], v[106:109]
	v_mfma_f32_16x16x32_bf16 v[106:109], v[168:171], v[214:217], v[106:109]
	v_mfma_f32_16x16x32_bf16 v[110:113], v[160:163], v[214:217], v[110:113]
	v_mfma_f32_16x16x32_bf16 v[110:113], v[144:147], v[210:213], v[110:113]
	v_mfma_f32_16x16x32_bf16 v[94:97], v[144:147], v[218:221], v[94:97]
	v_mfma_f32_16x16x32_bf16 v[94:97], v[160:163], v[222:225], v[94:97]
	v_mfma_f32_16x16x32_bf16 v[90:93], v[168:171], v[222:225], v[90:93]
	v_mfma_f32_16x16x32_bf16 v[90:93], v[164:167], v[218:221], v[90:93]
	v_mfma_f32_16x16x32_bf16 v[74:77], v[164:167], v[226:229], v[74:77]
	v_mfma_f32_16x16x32_bf16 v[74:77], v[168:171], v[230:233], v[74:77]
	v_mfma_f32_16x16x32_bf16 v[78:81], v[160:163], v[230:233], v[78:81]
	v_mfma_f32_16x16x32_bf16 v[78:81], v[144:147], v[226:229], v[78:81]
	v_mfma_f32_16x16x32_bf16 v[118:121], v[172:175], v[188:191], v[118:121]
	v_mfma_f32_16x16x32_bf16 v[118:121], v[176:179], v[206:209], v[118:121]
	v_mfma_f32_16x16x32_bf16 v[114:117], v[184:187], v[206:209], v[114:117]
	v_mfma_f32_16x16x32_bf16 v[114:117], v[180:183], v[188:191], v[114:117]
	v_mfma_f32_16x16x32_bf16 v[98:101], v[180:183], v[210:213], v[98:101]
	v_mfma_f32_16x16x32_bf16 v[98:101], v[184:187], v[214:217], v[98:101]
	v_mfma_f32_16x16x32_bf16 v[102:105], v[176:179], v[214:217], v[102:105]
	v_mfma_f32_16x16x32_bf16 v[102:105], v[172:175], v[210:213], v[102:105]
	v_mfma_f32_16x16x32_bf16 v[86:89], v[172:175], v[218:221], v[86:89]
	v_mfma_f32_16x16x32_bf16 v[86:89], v[176:179], v[222:225], v[86:89]
	v_mfma_f32_16x16x32_bf16 v[82:85], v[184:187], v[222:225], v[82:85]
	v_mfma_f32_16x16x32_bf16 v[82:85], v[180:183], v[218:221], v[82:85]
	v_mfma_f32_16x16x32_bf16 v[66:69], v[180:183], v[226:229], v[66:69]
	v_mfma_f32_16x16x32_bf16 v[66:69], v[184:187], v[230:233], v[66:69]
	v_mfma_f32_16x16x32_bf16 v[70:73], v[176:179], v[230:233], v[70:73]
	v_mfma_f32_16x16x32_bf16 v[70:73], v[172:175], v[226:229], v[70:73]
	s_barrier
	s_add_i32 s24, s72, s51
	v_lshl_add_u64 v[148:149], v[148:149], 0, s[38:39]
	s_mov_b32 m0, s24
	ds_read_b128 v[188:191], v152 offset:49152
	ds_read_b128 v[206:209], v152 offset:50176
	ds_read_b128 v[210:213], v152 offset:51200
	ds_read_b128 v[214:217], v152 offset:52224
	ds_read_b128 v[218:221], v152 offset:53248
	ds_read_b128 v[222:225], v152 offset:54272
	ds_read_b128 v[226:229], v152 offset:55296
	ds_read_b128 v[230:233], v152 offset:56320
	global_load_lds_dwordx4 v[148:149], off
	s_add_i32 m0, s24, 0x2000
	s_add_u32 s24, s42, 0x40080
	v_lshl_add_u64 v[148:149], v[234:235], 0, s[38:39]
	s_addc_u32 s25, s43, 0
	s_add_i32 s42, s73, s51
	global_load_lds_dwordx4 v[148:149], off
	v_lshl_add_u64 v[148:149], s[24:25], 0, v[132:133]
	s_mov_b32 m0, s42
	s_nop 0
	global_load_lds_dwordx4 v[148:149], off
	v_lshl_add_u64 v[148:149], s[24:25], 0, v[136:137]
	s_add_i32 m0, s42, 0x2000
	s_nop 0
	global_load_lds_dwordx4 v[148:149], off
	v_lshl_add_u64 v[148:149], s[26:27], 0, v[130:131]
	s_mov_b32 m0, s64
	s_nop 0
	global_load_lds_dwordx4 v[148:149], off
	v_lshl_add_u64 v[148:149], s[26:27], 0, v[134:135]
	s_mov_b32 m0, s65
	s_nop 0
	global_load_lds_dwordx4 v[148:149], off
	s_waitcnt vmcnt(8)
	.p2align 3
	s_waitcnt lgkmcnt(0)
	s_barrier
	v_mfma_f32_16x16x32_bf16 v[62:65], v[144:147], v[188:191], v[62:65]
	v_mfma_f32_16x16x32_bf16 v[62:65], v[160:163], v[206:209], v[62:65]
	v_mfma_f32_16x16x32_bf16 v[58:61], v[168:171], v[206:209], v[58:61]
	v_mfma_f32_16x16x32_bf16 v[58:61], v[164:167], v[188:191], v[58:61]
	v_mfma_f32_16x16x32_bf16 v[42:45], v[164:167], v[210:213], v[42:45]
	v_mfma_f32_16x16x32_bf16 v[42:45], v[168:171], v[214:217], v[42:45]
	v_mfma_f32_16x16x32_bf16 v[46:49], v[160:163], v[214:217], v[46:49]
	v_mfma_f32_16x16x32_bf16 v[46:49], v[144:147], v[210:213], v[46:49]
	v_mfma_f32_16x16x32_bf16 v[30:33], v[144:147], v[218:221], v[30:33]
	v_mfma_f32_16x16x32_bf16 v[30:33], v[160:163], v[222:225], v[30:33]
	v_mfma_f32_16x16x32_bf16 v[26:29], v[168:171], v[222:225], v[26:29]
	v_mfma_f32_16x16x32_bf16 v[26:29], v[164:167], v[218:221], v[26:29]
	v_mfma_f32_16x16x32_bf16 v[10:13], v[164:167], v[226:229], v[10:13]
	v_mfma_f32_16x16x32_bf16 v[10:13], v[168:171], v[230:233], v[10:13]
	v_mfma_f32_16x16x32_bf16 v[14:17], v[160:163], v[230:233], v[14:17]
	v_mfma_f32_16x16x32_bf16 v[14:17], v[144:147], v[226:229], v[14:17]
	v_mfma_f32_16x16x32_bf16 v[54:57], v[172:175], v[188:191], v[54:57]
	v_mfma_f32_16x16x32_bf16 v[54:57], v[176:179], v[206:209], v[54:57]
	v_mfma_f32_16x16x32_bf16 v[50:53], v[184:187], v[206:209], v[50:53]
	v_mfma_f32_16x16x32_bf16 v[50:53], v[180:183], v[188:191], v[50:53]
	v_mfma_f32_16x16x32_bf16 v[34:37], v[180:183], v[210:213], v[34:37]
	v_mfma_f32_16x16x32_bf16 v[34:37], v[184:187], v[214:217], v[34:37]
	v_mfma_f32_16x16x32_bf16 v[38:41], v[176:179], v[214:217], v[38:41]
	v_mfma_f32_16x16x32_bf16 v[38:41], v[172:175], v[210:213], v[38:41]
	v_mfma_f32_16x16x32_bf16 v[22:25], v[172:175], v[218:221], v[22:25]
	v_mfma_f32_16x16x32_bf16 v[22:25], v[176:179], v[222:225], v[22:25]
	v_mfma_f32_16x16x32_bf16 v[18:21], v[184:187], v[222:225], v[18:21]
	v_mfma_f32_16x16x32_bf16 v[18:21], v[180:183], v[218:221], v[18:21]
	v_mfma_f32_16x16x32_bf16 v[2:5], v[180:183], v[226:229], v[2:5]
	v_mfma_f32_16x16x32_bf16 v[2:5], v[184:187], v[230:233], v[2:5]
	v_mfma_f32_16x16x32_bf16 v[6:9], v[176:179], v[230:233], v[6:9]
	v_mfma_f32_16x16x32_bf16 v[6:9], v[172:175], v[226:229], v[6:9]
	s_barrier
	s_add_i32 s71, s71, 2
	s_add_u32 s69, s69, 0x100
	s_addc_u32 s70, s70, 0
	s_cmp_gt_u32 s71, 13
	s_mov_b64 s[24:25], s[2:3]
	s_cbranch_scc0 .LBB0_238

; #define PG8_STAGE(bufoff, gbase, voff) do { _Pragma("unroll") for (int _i = 0; _i < 2; ++_i) \
;         __builtin_amdgcn_global_load_lds((const unsigned*)((const char*)(gbase) + (voff)[_i]), (PG8_LAS unsigned*)(lds + (bufoff) + ldsw + _i * 8192), 16, 0, 0); } while (0)
; #define PG8_LDA(dst, b, h) do { _Pragma("unroll") for (int m = 0; m < 4; ++m) _Pragma("unroll") for (int k = 0; k < 2; ++k) dst[m][k] = *(const PG8_LAS bf16x8*)(lds + PG8_SA(b, h) + aoff + m * 2048 + k * 1024); } while (0)
; #define PG8_LDB(dst, b, h) do { _Pragma("unroll") for (int n = 0; n < 2; ++n) _Pragma("unroll") for (int k = 0; k < 2; ++k) dst[n][k] = *(const PG8_LAS bf16x8*)(lds + PG8_SB(b, h) + boff + n * 2048 + k * 1024); } while (0)
; #define PG8_WAIT_V(n) asm volatile("s_waitcnt vmcnt(" #n ")" ::: "memory")
; #define PG8_WAIT_L(n) asm volatile("s_waitcnt lgkmcnt(" #n ")" ::: "memory")
; #define PG8_BAR __builtin_amdgcn_s_barrier()
; #define PG8_SCHED __builtin_amdgcn_sched_barrier(0)
; template <class Epi, class Sched, bool ALIGN_EPI = false, bool SP2 = false>
; __device__ __forceinline__ void gemm_phase(PG8_LAS unsigned char* lds, const Gemm g, const Sched& S, const Epi& E) {
;     ...
;         const bool has_next = S.next(ui + 1, nxt);
;         const char* nA = has_next ? (const char*)g.A + (size_t)nxt.pm * tstep : cA; const char* nB = has_next ? (const char*)g.Bt + (size_t)nxt.pn * tstep : cB;
;         for (int t = 0; t < nt; t += 2) {
;             const bool last = (t == nt - 2);
;             const char* a1 = cA + (size_t)(t + 1) * kstepA;
;             const char* a2 = last ? nA : cA + (size_t)(t + 2) * kstepA; const char* b2 = last ? nB : cB + (size_t)(t + 2) * kstep;
;             const char* a3 = a2 + kstepA; const char* b3 = b2 + kstep;
;             if (last && has_next) S.a_ready(nxt);
;             if constexpr (SP2) {
;             PG8_LDB(B0, 0, 0); PG8_LDB(B1, 0, 1); PG8_SCHED; PG8_LDA(At, 0, 0); PG8_STAGE(PG8_SA(1, 1), a1 + hstep, voffA);
;             PG8_WAIT_V(8); PG8_WAIT_L(0); PG8_BAR; PG8_MMA(0, 0, At, B0); PG8_MMA(0, 1, At, B1); PG8_BAR; PG8_SCHED;
;             PG8_LDA(At, 0, 1); PG8_STAGE(PG8_SB(0, 0), b2, voffB); PG8_STAGE(PG8_SB(0, 1), b2 + hstep, voffB); PG8_STAGE(PG8_SA(0, 0), a2, voffA);
;             PG8_WAIT_V(8); PG8_WAIT_L(0); PG8_BAR; PG8_MMA(1, 0, At, B0); PG8_MMA(1, 1, At, B1); PG8_BAR; PG8_SCHED;
.LBB0_309:
	s_add_u32 s47, s24, 0x100
	s_addc_u32 s48, s25, 0
	s_add_u32 s2, s26, 0x4000
	s_addc_u32 s3, s27, 0
	s_mov_b32 s24, 0
	s_add_i32 s49, s24, 2
	s_add_u32 s25, s2, 0x4000
	s_addc_u32 s26, s3, 0
	s_cmp_eq_u32 s59, s24
	s_cselect_b32 s27, s9, s26
	s_cselect_b32 s26, s8, s25
	s_cselect_b32 s66, s44, s47
	s_cselect_b32 s67, s45, s48
	s_add_u32 s24, s26, 0x4000
	s_addc_u32 s25, s27, 0
	s_add_i32 s65, 0, 0x14000
	v_add_u32_e32 v142, s76, v187
	v_add_u32_e32 v167, s65, v187
	ds_read_b128 v[130:133], v142
	ds_read_b128 v[134:137], v142 offset:1024
	ds_read_b128 v[138:141], v142 offset:2048
	ds_read_b128 v[142:145], v142 offset:3072
	ds_read_b128 v[146:149], v167
	ds_read_b128 v[150:153], v167 offset:1024
	ds_read_b128 v[206:209], v167 offset:2048
	ds_read_b128 v[210:213], v167 offset:3072
	v_lshl_add_u64 v[184:185], s[2:3], 0, v[182:183]
	s_add_i32 m0, s51, 0xc000
	ds_read_b128 v[214:217], v188
	ds_read_b128 v[218:221], v188 offset:1024
	ds_read_b128 v[222:225], v188 offset:2048
	ds_read_b128 v[226:229], v188 offset:3072
	ds_read_b128 v[230:233], v188 offset:4096
	ds_read_b128 v[234:237], v188 offset:5120
	ds_read_b128 v[238:241], v188 offset:6144
	ds_read_b128 v[242:245], v188 offset:7168
	global_load_lds_dwordx4 v[184:185], off
	v_lshl_add_u64 v[184:185], s[2:3], 0, v[180:181]
	s_add_i32 m0, s51, 0xe000
	s_nop 0
	global_load_lds_dwordx4 v[184:185], off
	s_waitcnt vmcnt(8)
	.p2align 3
	s_waitcnt lgkmcnt(0)
	s_barrier
	v_mfma_f32_16x16x32_bf16 v[126:129], v[130:133], v[214:217], 0
	v_mfma_f32_16x16x32_bf16 v[126:129], v[134:137], v[218:221], v[126:129]
	v_mfma_f32_16x16x32_bf16 v[122:125], v[142:145], v[218:221], 0
	v_mfma_f32_16x16x32_bf16 v[122:125], v[138:141], v[214:217], v[122:125]
	v_mfma_f32_16x16x32_bf16 v[106:109], v[138:141], v[222:225], 0
	v_mfma_f32_16x16x32_bf16 v[106:109], v[142:145], v[226:229], v[106:109]
	v_mfma_f32_16x16x32_bf16 v[110:113], v[134:137], v[226:229], 0
	v_mfma_f32_16x16x32_bf16 v[110:113], v[130:133], v[222:225], v[110:113]
	v_mfma_f32_16x16x32_bf16 v[94:97], v[130:133], v[230:233], 0
	v_mfma_f32_16x16x32_bf16 v[94:97], v[134:137], v[234:237], v[94:97]
	v_mfma_f32_16x16x32_bf16 v[90:93], v[142:145], v[234:237], 0
	v_mfma_f32_16x16x32_bf16 v[90:93], v[138:141], v[230:233], v[90:93]
	v_mfma_f32_16x16x32_bf16 v[74:77], v[138:141], v[238:241], 0
	v_mfma_f32_16x16x32_bf16 v[74:77], v[142:145], v[242:245], v[74:77]
	v_mfma_f32_16x16x32_bf16 v[78:81], v[134:137], v[242:245], 0
	v_mfma_f32_16x16x32_bf16 v[78:81], v[130:133], v[238:241], v[78:81]
	v_mfma_f32_16x16x32_bf16 v[118:121], v[146:149], v[214:217], 0
	v_mfma_f32_16x16x32_bf16 v[118:121], v[150:153], v[218:221], v[118:121]
	v_mfma_f32_16x16x32_bf16 v[114:117], v[210:213], v[218:221], 0
	v_mfma_f32_16x16x32_bf16 v[114:117], v[206:209], v[214:217], v[114:117]
	v_mfma_f32_16x16x32_bf16 v[98:101], v[206:209], v[222:225], 0
	v_mfma_f32_16x16x32_bf16 v[98:101], v[210:213], v[226:229], v[98:101]
	v_mfma_f32_16x16x32_bf16 v[102:105], v[150:153], v[226:229], 0
	v_mfma_f32_16x16x32_bf16 v[102:105], v[146:149], v[222:225], v[102:105]
	v_mfma_f32_16x16x32_bf16 v[86:89], v[146:149], v[230:233], 0
	v_mfma_f32_16x16x32_bf16 v[86:89], v[150:153], v[234:237], v[86:89]
	v_mfma_f32_16x16x32_bf16 v[82:85], v[210:213], v[234:237], 0
	v_mfma_f32_16x16x32_bf16 v[82:85], v[206:209], v[230:233], v[82:85]
	v_mfma_f32_16x16x32_bf16 v[66:69], v[206:209], v[238:241], 0
	v_mfma_f32_16x16x32_bf16 v[66:69], v[210:213], v[242:245], v[66:69]
	v_mfma_f32_16x16x32_bf16 v[70:73], v[150:153], v[242:245], 0
	v_mfma_f32_16x16x32_bf16 v[70:73], v[146:149], v[238:241], v[70:73]
	s_barrier
	s_add_i32 s68, s76, s50
	v_lshl_add_u64 v[184:185], s[66:67], 0, v[0:1]
	s_mov_b32 m0, s68
	ds_read_b128 v[214:217], v188 offset:16384
	ds_read_b128 v[218:221], v188 offset:17408
	ds_read_b128 v[222:225], v188 offset:18432
	ds_read_b128 v[226:229], v188 offset:19456
	ds_read_b128 v[230:233], v188 offset:20480
	ds_read_b128 v[234:237], v188 offset:21504
	ds_read_b128 v[238:241], v188 offset:22528
	ds_read_b128 v[242:245], v188 offset:23552
	global_load_lds_dwordx4 v[184:185], off
	s_add_i32 m0, s68, 0x2000
	v_lshl_add_u64 v[190:191], s[66:67], 0, v[164:165]
	s_add_u32 s66, s66, s12
	s_addc_u32 s67, s67, 0
	s_add_i32 s65, s65, s50
	global_load_lds_dwordx4 v[190:191], off
	v_lshl_add_u64 v[246:247], s[66:67], 0, v[0:1]
	s_mov_b32 m0, s65
	v_lshl_add_u64 v[248:249], s[66:67], 0, v[164:165]
	global_load_lds_dwordx4 v[246:247], off
	s_add_i32 m0, s65, 0x2000
	v_lshl_add_u64 v[250:251], s[26:27], 0, v[160:161]
	global_load_lds_dwordx4 v[248:249], off
	s_mov_b32 m0, s51
	s_nop 0
	global_load_lds_dwordx4 v[250:251], off
	v_lshl_add_u64 v[250:251], s[26:27], 0, v[162:163]
	s_mov_b32 m0, s52
	s_nop 0
	global_load_lds_dwordx4 v[250:251], off
	s_waitcnt vmcnt(8)
	.p2align 3
	s_waitcnt lgkmcnt(0)
	s_barrier
; #define PG8_STAGE(bufoff, gbase, voff) do { _Pragma("unroll") for (int _i = 0; _i < 2; ++_i) \
;         __builtin_amdgcn_global_load_lds((const unsigned*)((const char*)(gbase) + (voff)[_i]), (PG8_LAS unsigned*)(lds + (bufoff) + ldsw + _i * 8192), 16, 0, 0); } while (0)
; #define PG8_LDA(dst, b, h) do { _Pragma("unroll") for (int m = 0; m < 4; ++m) _Pragma("unroll") for (int k = 0; k < 2; ++k) dst[m][k] = *(const PG8_LAS bf16x8*)(lds + PG8_SA(b, h) + aoff + m * 2048 + k * 1024); } while (0)
; #define PG8_LDB(dst, b, h) do { _Pragma("unroll") for (int n = 0; n < 2; ++n) _Pragma("unroll") for (int k = 0; k < 2; ++k) dst[n][k] = *(const PG8_LAS bf16x8*)(lds + PG8_SB(b, h) + boff + n * 2048 + k * 1024); } while (0)
; #define PG8_MMA(ai, bj, At, Bt) do { __builtin_amdgcn_s_setprio(1); _Pragma("unroll") for (int m = 0; m < 4; ++m) _Pragma("unroll") for (int n = 0; n < 2; ++n) _Pragma("unroll") for (int k = 0; k < 2; ++k) \
;         acc[ai][bj][m][n] = __builtin_amdgcn_mfma_f32_16x16x32_bf16(Bt[n][k], At[m][k], acc[ai][bj][m][n], 0, 0, 0); __builtin_amdgcn_s_setprio(0); } while (0)
; #define PG8_WAIT_V(n) asm volatile("s_waitcnt vmcnt(" #n ")" ::: "memory")
; #define PG8_WAIT_L(n) asm volatile("s_waitcnt lgkmcnt(" #n ")" ::: "memory")
; #define PG8_BAR __builtin_amdgcn_s_barrier()
; #define PG8_SCHED __builtin_amdgcn_sched_barrier(0)
; template <class Epi, class Sched, bool ALIGN_EPI = false, bool SP2 = false>
; __device__ __forceinline__ void gemm_phase(PG8_LAS unsigned char* lds, const Gemm g, const Sched& S, const Epi& E) {
;     ...
;             PG8_WAIT_V(8); PG8_WAIT_L(0); PG8_BAR; PG8_MMA(1, 0, At, B0); PG8_MMA(1, 1, At, B1); PG8_BAR; PG8_SCHED;
;             PG8_LDB(B0, 1, 0); PG8_LDB(B1, 1, 1); PG8_SCHED; PG8_LDA(At, 1, 0); PG8_STAGE(PG8_SA(0, 1), a2 + hstep, voffA);
;             PG8_WAIT_V(8); PG8_WAIT_L(0); PG8_BAR; PG8_MMA(0, 0, At, B0); PG8_MMA(0, 1, At, B1); PG8_BAR; PG8_SCHED;
	v_mfma_f32_16x16x32_bf16 v[62:65], v[130:133], v[214:217], 0
	v_mfma_f32_16x16x32_bf16 v[62:65], v[134:137], v[218:221], v[62:65]
	v_mfma_f32_16x16x32_bf16 v[58:61], v[142:145], v[218:221], 0
	v_mfma_f32_16x16x32_bf16 v[58:61], v[138:141], v[214:217], v[58:61]
	v_mfma_f32_16x16x32_bf16 v[42:45], v[138:141], v[222:225], 0
	v_mfma_f32_16x16x32_bf16 v[42:45], v[142:145], v[226:229], v[42:45]
	v_mfma_f32_16x16x32_bf16 v[46:49], v[134:137], v[226:229], 0
	v_mfma_f32_16x16x32_bf16 v[46:49], v[130:133], v[222:225], v[46:49]
	v_mfma_f32_16x16x32_bf16 v[30:33], v[130:133], v[230:233], 0
	v_mfma_f32_16x16x32_bf16 v[30:33], v[134:137], v[234:237], v[30:33]
	v_mfma_f32_16x16x32_bf16 v[26:29], v[142:145], v[234:237], 0
	v_mfma_f32_16x16x32_bf16 v[26:29], v[138:141], v[230:233], v[26:29]
	v_mfma_f32_16x16x32_bf16 v[10:13], v[138:141], v[238:241], 0
	v_mfma_f32_16x16x32_bf16 v[10:13], v[142:145], v[242:245], v[10:13]
	v_mfma_f32_16x16x32_bf16 v[14:17], v[134:137], v[242:245], 0
	v_mfma_f32_16x16x32_bf16 v[14:17], v[130:133], v[238:241], v[14:17]
	v_mfma_f32_16x16x32_bf16 v[54:57], v[146:149], v[214:217], 0
	v_mfma_f32_16x16x32_bf16 v[54:57], v[150:153], v[218:221], v[54:57]
	v_mfma_f32_16x16x32_bf16 v[50:53], v[210:213], v[218:221], 0
	v_mfma_f32_16x16x32_bf16 v[50:53], v[206:209], v[214:217], v[50:53]
	v_mfma_f32_16x16x32_bf16 v[34:37], v[206:209], v[222:225], 0
	v_mfma_f32_16x16x32_bf16 v[34:37], v[210:213], v[226:229], v[34:37]
	v_mfma_f32_16x16x32_bf16 v[38:41], v[150:153], v[226:229], 0
	v_mfma_f32_16x16x32_bf16 v[38:41], v[146:149], v[222:225], v[38:41]
	v_mfma_f32_16x16x32_bf16 v[22:25], v[146:149], v[230:233], 0
	v_mfma_f32_16x16x32_bf16 v[22:25], v[150:153], v[234:237], v[22:25]
	v_mfma_f32_16x16x32_bf16 v[18:21], v[210:213], v[234:237], 0
	v_mfma_f32_16x16x32_bf16 v[18:21], v[206:209], v[230:233], v[18:21]
	v_mfma_f32_16x16x32_bf16 v[2:5], v[206:209], v[238:241], 0
	v_mfma_f32_16x16x32_bf16 v[2:5], v[210:213], v[242:245], v[2:5]
	v_mfma_f32_16x16x32_bf16 v[6:9], v[150:153], v[242:245], 0
	v_mfma_f32_16x16x32_bf16 v[6:9], v[146:149], v[238:241], v[6:9]
	s_barrier
	s_add_i32 s65, 0, 0x18000
	s_add_i32 s66, 0, 0x1c000
	v_add_u32_e32 v142, s65, v187
	v_add_u32_e32 v167, s66, v187
	ds_read_b128 v[130:133], v142
	ds_read_b128 v[134:137], v142 offset:1024
	ds_read_b128 v[138:141], v142 offset:2048
	ds_read_b128 v[142:145], v142 offset:3072
	ds_read_b128 v[146:149], v167
	ds_read_b128 v[150:153], v167 offset:1024
	ds_read_b128 v[206:209], v167 offset:2048
	ds_read_b128 v[210:213], v167 offset:3072
	s_add_u32 s26, s26, s12
	s_addc_u32 s27, s27, 0
	s_mov_b32 m0, s53
	v_lshl_add_u64 v[250:251], s[26:27], 0, v[160:161]
	ds_read_b128 v[214:217], v188 offset:32768
	ds_read_b128 v[218:221], v188 offset:33792
	ds_read_b128 v[222:225], v188 offset:34816
	ds_read_b128 v[226:229], v188 offset:35840
	ds_read_b128 v[230:233], v188 offset:36864
	ds_read_b128 v[234:237], v188 offset:37888
	ds_read_b128 v[238:241], v188 offset:38912
	ds_read_b128 v[242:245], v188 offset:39936
	global_load_lds_dwordx4 v[250:251], off
	v_lshl_add_u64 v[250:251], s[26:27], 0, v[162:163]
	s_mov_b32 m0, s54
	s_nop 0
	global_load_lds_dwordx4 v[250:251], off
	s_waitcnt vmcnt(8)
	.p2align 3
	s_waitcnt lgkmcnt(0)
	s_barrier
	v_mfma_f32_16x16x32_bf16 v[126:129], v[130:133], v[214:217], v[126:129]
	v_mfma_f32_16x16x32_bf16 v[126:129], v[134:137], v[218:221], v[126:129]
	v_mfma_f32_16x16x32_bf16 v[122:125], v[142:145], v[218:221], v[122:125]
	v_mfma_f32_16x16x32_bf16 v[122:125], v[138:141], v[214:217], v[122:125]
	v_mfma_f32_16x16x32_bf16 v[106:109], v[138:141], v[222:225], v[106:109]
	v_mfma_f32_16x16x32_bf16 v[106:109], v[142:145], v[226:229], v[106:109]
	v_mfma_f32_16x16x32_bf16 v[110:113], v[134:137], v[226:229], v[110:113]
	v_mfma_f32_16x16x32_bf16 v[110:113], v[130:133], v[222:225], v[110:113]
	v_mfma_f32_16x16x32_bf16 v[94:97], v[130:133], v[230:233], v[94:97]
	v_mfma_f32_16x16x32_bf16 v[94:97], v[134:137], v[234:237], v[94:97]
	v_mfma_f32_16x16x32_bf16 v[90:93], v[142:145], v[234:237], v[90:93]
	v_mfma_f32_16x16x32_bf16 v[90:93], v[138:141], v[230:233], v[90:93]
	v_mfma_f32_16x16x32_bf16 v[74:77], v[138:141], v[238:241], v[74:77]
	v_mfma_f32_16x16x32_bf16 v[74:77], v[142:145], v[242:245], v[74:77]
	v_mfma_f32_16x16x32_bf16 v[78:81], v[134:137], v[242:245], v[78:81]
	v_mfma_f32_16x16x32_bf16 v[78:81], v[130:133], v[238:241], v[78:81]
	v_mfma_f32_16x16x32_bf16 v[118:121], v[146:149], v[214:217], v[118:121]
	v_mfma_f32_16x16x32_bf16 v[118:121], v[150:153], v[218:221], v[118:121]
	v_mfma_f32_16x16x32_bf16 v[114:117], v[210:213], v[218:221], v[114:117]
	v_mfma_f32_16x16x32_bf16 v[114:117], v[206:209], v[214:217], v[114:117]
	v_mfma_f32_16x16x32_bf16 v[98:101], v[206:209], v[222:225], v[98:101]
	v_mfma_f32_16x16x32_bf16 v[98:101], v[210:213], v[226:229], v[98:101]
	v_mfma_f32_16x16x32_bf16 v[102:105], v[150:153], v[226:229], v[102:105]
	v_mfma_f32_16x16x32_bf16 v[102:105], v[146:149], v[222:225], v[102:105]
	v_mfma_f32_16x16x32_bf16 v[86:89], v[146:149], v[230:233], v[86:89]
	v_mfma_f32_16x16x32_bf16 v[86:89], v[150:153], v[234:237], v[86:89]
	v_mfma_f32_16x16x32_bf16 v[82:85], v[210:213], v[234:237], v[82:85]
	v_mfma_f32_16x16x32_bf16 v[82:85], v[206:209], v[230:233], v[82:85]
	v_mfma_f32_16x16x32_bf16 v[66:69], v[206:209], v[238:241], v[66:69]
	v_mfma_f32_16x16x32_bf16 v[66:69], v[210:213], v[242:245], v[66:69]
	v_mfma_f32_16x16x32_bf16 v[70:73], v[150:153], v[242:245], v[70:73]
	v_mfma_f32_16x16x32_bf16 v[70:73], v[146:149], v[238:241], v[70:73]
	s_barrier
; #define PG8_STAGE(bufoff, gbase, voff) do { _Pragma("unroll") for (int _i = 0; _i < 2; ++_i) \
;         __builtin_amdgcn_global_load_lds((const unsigned*)((const char*)(gbase) + (voff)[_i]), (PG8_LAS unsigned*)(lds + (bufoff) + ldsw + _i * 8192), 16, 0, 0); } while (0)
; #define PG8_LDA(dst, b, h) do { _Pragma("unroll") for (int m = 0; m < 4; ++m) _Pragma("unroll") for (int k = 0; k < 2; ++k) dst[m][k] = *(const PG8_LAS bf16x8*)(lds + PG8_SA(b, h) + aoff + m * 2048 + k * 1024); } while (0)
; #define PG8_LDB(dst, b, h) do { _Pragma("unroll") for (int n = 0; n < 2; ++n) _Pragma("unroll") for (int k = 0; k < 2; ++k) dst[n][k] = *(const PG8_LAS bf16x8*)(lds + PG8_SB(b, h) + boff + n * 2048 + k * 1024); } while (0)
; template <class Epi, class Sched, bool ALIGN_EPI = false, bool SP2 = false>
; __device__ __forceinline__ void gemm_phase(PG8_LAS unsigned char* lds, const Gemm g, const Sched& S, const Epi& E) {
;     ...
;         for (int t = 0; t < nt; t += 2) {
;             const bool last = (t == nt - 2);
;             const char* a1 = cA + (size_t)(t + 1) * kstepA;
;             const char* a2 = last ? nA : cA + (size_t)(t + 2) * kstepA; const char* b2 = last ? nB : cB + (size_t)(t + 2) * kstep;
;             const char* a3 = a2 + kstepA; const char* b3 = b2 + kstep;
;             if (last && has_next) S.a_ready(nxt);
;             if constexpr (SP2) {
;             PG8_LDB(B0, 0, 0); PG8_LDB(B1, 0, 1); PG8_SCHED; PG8_LDA(At, 0, 0); PG8_STAGE(PG8_SA(1, 1), a1 + hstep, voffA);
;             PG8_WAIT_V(8); PG8_WAIT_L(0); PG8_BAR; PG8_MMA(0, 0, At, B0); PG8_MMA(0, 1, At, B1); PG8_BAR; PG8_SCHED;
;             PG8_LDA(At, 0, 1); PG8_STAGE(PG8_SB(0, 0), b2, voffB); PG8_STAGE(PG8_SB(0, 1), b2 + hstep, voffB); PG8_STAGE(PG8_SA(0, 0), a2, voffA);
;             PG8_WAIT_V(8); PG8_WAIT_L(0); PG8_BAR; PG8_MMA(1, 0, At, B0); PG8_MMA(1, 1, At, B1); PG8_BAR; PG8_SCHED;
;             PG8_LDB(B0, 1, 0); PG8_LDB(B1, 1, 1); PG8_SCHED; PG8_LDA(At, 1, 0); PG8_STAGE(PG8_SA(0, 1), a2 + hstep, voffA);
;             PG8_WAIT_V(8); PG8_WAIT_L(0); PG8_BAR; PG8_MMA(0, 0, At, B0); PG8_MMA(0, 1, At, B1); PG8_BAR; PG8_SCHED;
;             PG8_LDA(At, 1, 1); PG8_STAGE(PG8_SB(1, 0), b3, voffB); PG8_STAGE(PG8_SB(1, 1), b3 + hstep, voffB); PG8_STAGE(PG8_SA(1, 0), a3, voffA);
;             PG8_WAIT_V(8); PG8_WAIT_L(0); PG8_BAR; PG8_MMA(1, 0, At, B0); PG8_MMA(1, 1, At, B1); PG8_BAR; PG8_SCHED;
	s_add_i32 s26, s65, s50
	v_lshl_add_u64 v[184:185], v[184:185], 0, s[38:39]
	s_mov_b32 m0, s26
	ds_read_b128 v[214:217], v188 offset:49152
	ds_read_b128 v[218:221], v188 offset:50176
	ds_read_b128 v[222:225], v188 offset:51200
	ds_read_b128 v[226:229], v188 offset:52224
	ds_read_b128 v[230:233], v188 offset:53248
	ds_read_b128 v[234:237], v188 offset:54272
	ds_read_b128 v[238:241], v188 offset:55296
	ds_read_b128 v[242:245], v188 offset:56320
	global_load_lds_dwordx4 v[184:185], off
	v_lshl_add_u64 v[184:185], v[190:191], 0, s[38:39]
	s_add_i32 m0, s26, 0x2000
	s_add_i32 s26, s66, s50
	global_load_lds_dwordx4 v[184:185], off
	v_lshl_add_u64 v[184:185], v[246:247], 0, s[38:39]
	s_mov_b32 m0, s26
	s_nop 0
	global_load_lds_dwordx4 v[184:185], off
	v_lshl_add_u64 v[184:185], v[248:249], 0, s[38:39]
	s_add_i32 m0, s26, 0x2000
	s_nop 0
	global_load_lds_dwordx4 v[184:185], off
	v_lshl_add_u64 v[184:185], s[24:25], 0, v[160:161]
	s_mov_b32 m0, s56
	s_nop 0
	global_load_lds_dwordx4 v[184:185], off
	v_lshl_add_u64 v[184:185], s[24:25], 0, v[162:163]
	s_mov_b32 m0, s57
	s_nop 0
	global_load_lds_dwordx4 v[184:185], off
	s_waitcnt vmcnt(8)
	.p2align 3
	s_waitcnt lgkmcnt(0)
	s_barrier
	v_mfma_f32_16x16x32_bf16 v[62:65], v[130:133], v[214:217], v[62:65]
	v_mfma_f32_16x16x32_bf16 v[62:65], v[134:137], v[218:221], v[62:65]
	v_mfma_f32_16x16x32_bf16 v[58:61], v[142:145], v[218:221], v[58:61]
	v_mfma_f32_16x16x32_bf16 v[58:61], v[138:141], v[214:217], v[58:61]
	v_mfma_f32_16x16x32_bf16 v[42:45], v[138:141], v[222:225], v[42:45]
	v_mfma_f32_16x16x32_bf16 v[42:45], v[142:145], v[226:229], v[42:45]
	v_mfma_f32_16x16x32_bf16 v[46:49], v[134:137], v[226:229], v[46:49]
	v_mfma_f32_16x16x32_bf16 v[46:49], v[130:133], v[222:225], v[46:49]
	v_mfma_f32_16x16x32_bf16 v[30:33], v[130:133], v[230:233], v[30:33]
	v_mfma_f32_16x16x32_bf16 v[30:33], v[134:137], v[234:237], v[30:33]
	v_mfma_f32_16x16x32_bf16 v[26:29], v[142:145], v[234:237], v[26:29]
	v_mfma_f32_16x16x32_bf16 v[26:29], v[138:141], v[230:233], v[26:29]
	v_mfma_f32_16x16x32_bf16 v[10:13], v[138:141], v[238:241], v[10:13]
	v_mfma_f32_16x16x32_bf16 v[10:13], v[142:145], v[242:245], v[10:13]
	v_mfma_f32_16x16x32_bf16 v[14:17], v[134:137], v[242:245], v[14:17]
	v_mfma_f32_16x16x32_bf16 v[14:17], v[130:133], v[238:241], v[14:17]
	v_mfma_f32_16x16x32_bf16 v[54:57], v[146:149], v[214:217], v[54:57]
	v_mfma_f32_16x16x32_bf16 v[54:57], v[150:153], v[218:221], v[54:57]
	v_mfma_f32_16x16x32_bf16 v[50:53], v[210:213], v[218:221], v[50:53]
	v_mfma_f32_16x16x32_bf16 v[50:53], v[206:209], v[214:217], v[50:53]
	v_mfma_f32_16x16x32_bf16 v[34:37], v[206:209], v[222:225], v[34:37]
	v_mfma_f32_16x16x32_bf16 v[34:37], v[210:213], v[226:229], v[34:37]
	v_mfma_f32_16x16x32_bf16 v[38:41], v[150:153], v[226:229], v[38:41]
	v_mfma_f32_16x16x32_bf16 v[38:41], v[146:149], v[222:225], v[38:41]
	v_mfma_f32_16x16x32_bf16 v[22:25], v[146:149], v[230:233], v[22:25]
	v_mfma_f32_16x16x32_bf16 v[22:25], v[150:153], v[234:237], v[22:25]
	v_mfma_f32_16x16x32_bf16 v[18:21], v[210:213], v[234:237], v[18:21]
	v_mfma_f32_16x16x32_bf16 v[18:21], v[206:209], v[230:233], v[18:21]
	v_mfma_f32_16x16x32_bf16 v[2:5], v[206:209], v[238:241], v[2:5]
	v_mfma_f32_16x16x32_bf16 v[2:5], v[210:213], v[242:245], v[2:5]
	v_mfma_f32_16x16x32_bf16 v[6:9], v[150:153], v[242:245], v[6:9]
	v_mfma_f32_16x16x32_bf16 v[6:9], v[146:149], v[238:241], v[6:9]
	s_barrier
	s_add_u32 s47, s47, 0x100
	s_addc_u32 s48, s48, 0
	s_add_u32 s2, s2, 0x8000
	s_addc_u32 s3, s3, 0
	s_cmp_ge_u32 s49, s55
	s_mov_b32 s24, s49
	s_cbranch_scc1 .Lpeel_exit_1
.LBB0_310:
	s_add_i32 s49, s24, 2
	s_add_u32 s25, s2, 0x4000
	s_addc_u32 s26, s3, 0
	s_cmp_eq_u32 s59, s24
	s_cselect_b32 s27, s9, s26
	s_cselect_b32 s26, s8, s25
	s_cselect_b32 s66, s44, s47
	s_cselect_b32 s67, s45, s48
	s_add_u32 s24, s26, 0x4000
	s_addc_u32 s25, s27, 0
	s_add_i32 s65, 0, 0x14000
	v_add_u32_e32 v142, s76, v187
	v_add_u32_e32 v167, s65, v187
	ds_read_b128 v[130:133], v142
	ds_read_b128 v[134:137], v142 offset:1024
	ds_read_b128 v[138:141], v142 offset:2048
	ds_read_b128 v[142:145], v142 offset:3072
	ds_read_b128 v[146:149], v167
	ds_read_b128 v[150:153], v167 offset:1024
	ds_read_b128 v[206:209], v167 offset:2048
	ds_read_b128 v[210:213], v167 offset:3072
	v_lshl_add_u64 v[184:185], s[2:3], 0, v[182:183]
	s_add_i32 m0, s51, 0xc000
	ds_read_b128 v[214:217], v188
	ds_read_b128 v[218:221], v188 offset:1024
	ds_read_b128 v[222:225], v188 offset:2048
	ds_read_b128 v[226:229], v188 offset:3072
	ds_read_b128 v[230:233], v188 offset:4096
	ds_read_b128 v[234:237], v188 offset:5120
	ds_read_b128 v[238:241], v188 offset:6144
	ds_read_b128 v[242:245], v188 offset:7168
	global_load_lds_dwordx4 v[184:185], off
	v_lshl_add_u64 v[184:185], s[2:3], 0, v[180:181]
	s_add_i32 m0, s51, 0xe000
	s_nop 0
	global_load_lds_dwordx4 v[184:185], off
	s_waitcnt vmcnt(8)
	.p2align 3
	s_waitcnt lgkmcnt(0)
	s_barrier
; #define PG8_STAGE(bufoff, gbase, voff) do { _Pragma("unroll") for (int _i = 0; _i < 2; ++_i) \
;         __builtin_amdgcn_global_load_lds((const unsigned*)((const char*)(gbase) + (voff)[_i]), (PG8_LAS unsigned*)(lds + (bufoff) + ldsw + _i * 8192), 16, 0, 0); } while (0)
; #define PG8_LDA(dst, b, h) do { _Pragma("unroll") for (int m = 0; m < 4; ++m) _Pragma("unroll") for (int k = 0; k < 2; ++k) dst[m][k] = *(const PG8_LAS bf16x8*)(lds + PG8_SA(b, h) + aoff + m * 2048 + k * 1024); } while (0)
; #define PG8_MMA(ai, bj, At, Bt) do { __builtin_amdgcn_s_setprio(1); _Pragma("unroll") for (int m = 0; m < 4; ++m) _Pragma("unroll") for (int n = 0; n < 2; ++n) _Pragma("unroll") for (int k = 0; k < 2; ++k) \
;         acc[ai][bj][m][n] = __builtin_amdgcn_mfma_f32_16x16x32_bf16(Bt[n][k], At[m][k], acc[ai][bj][m][n], 0, 0, 0); __builtin_amdgcn_s_setprio(0); } while (0)
; #define PG8_WAIT_V(n) asm volatile("s_waitcnt vmcnt(" #n ")" ::: "memory")
; #define PG8_WAIT_L(n) asm volatile("s_waitcnt lgkmcnt(" #n ")" ::: "memory")
; #define PG8_BAR __builtin_amdgcn_s_barrier()
; #define PG8_SCHED __builtin_amdgcn_sched_barrier(0)
; template <class Epi, class Sched, bool ALIGN_EPI = false, bool SP2 = false>
; __device__ __forceinline__ void gemm_phase(PG8_LAS unsigned char* lds, const Gemm g, const Sched& S, const Epi& E) {
;     ...
;             PG8_WAIT_V(8); PG8_WAIT_L(0); PG8_BAR; PG8_MMA(0, 0, At, B0); PG8_MMA(0, 1, At, B1); PG8_BAR; PG8_SCHED;
;             PG8_LDA(At, 0, 1); PG8_STAGE(PG8_SB(0, 0), b2, voffB); PG8_STAGE(PG8_SB(0, 1), b2 + hstep, voffB); PG8_STAGE(PG8_SA(0, 0), a2, voffA);
;             PG8_WAIT_V(8); PG8_WAIT_L(0); PG8_BAR; PG8_MMA(1, 0, At, B0); PG8_MMA(1, 1, At, B1); PG8_BAR; PG8_SCHED;
	v_mfma_f32_16x16x32_bf16 v[126:129], v[130:133], v[214:217], v[126:129]
	v_mfma_f32_16x16x32_bf16 v[126:129], v[134:137], v[218:221], v[126:129]
	v_mfma_f32_16x16x32_bf16 v[122:125], v[142:145], v[218:221], v[122:125]
	v_mfma_f32_16x16x32_bf16 v[122:125], v[138:141], v[214:217], v[122:125]
	v_mfma_f32_16x16x32_bf16 v[106:109], v[138:141], v[222:225], v[106:109]
	v_mfma_f32_16x16x32_bf16 v[106:109], v[142:145], v[226:229], v[106:109]
	v_mfma_f32_16x16x32_bf16 v[110:113], v[134:137], v[226:229], v[110:113]
	v_mfma_f32_16x16x32_bf16 v[110:113], v[130:133], v[222:225], v[110:113]
	v_mfma_f32_16x16x32_bf16 v[94:97], v[130:133], v[230:233], v[94:97]
	v_mfma_f32_16x16x32_bf16 v[94:97], v[134:137], v[234:237], v[94:97]
	v_mfma_f32_16x16x32_bf16 v[90:93], v[142:145], v[234:237], v[90:93]
	v_mfma_f32_16x16x32_bf16 v[90:93], v[138:141], v[230:233], v[90:93]
	v_mfma_f32_16x16x32_bf16 v[74:77], v[138:141], v[238:241], v[74:77]
	v_mfma_f32_16x16x32_bf16 v[74:77], v[142:145], v[242:245], v[74:77]
	v_mfma_f32_16x16x32_bf16 v[78:81], v[134:137], v[242:245], v[78:81]
	v_mfma_f32_16x16x32_bf16 v[78:81], v[130:133], v[238:241], v[78:81]
	v_mfma_f32_16x16x32_bf16 v[118:121], v[146:149], v[214:217], v[118:121]
	v_mfma_f32_16x16x32_bf16 v[118:121], v[150:153], v[218:221], v[118:121]
	v_mfma_f32_16x16x32_bf16 v[114:117], v[210:213], v[218:221], v[114:117]
	v_mfma_f32_16x16x32_bf16 v[114:117], v[206:209], v[214:217], v[114:117]
	v_mfma_f32_16x16x32_bf16 v[98:101], v[206:209], v[222:225], v[98:101]
	v_mfma_f32_16x16x32_bf16 v[98:101], v[210:213], v[226:229], v[98:101]
	v_mfma_f32_16x16x32_bf16 v[102:105], v[150:153], v[226:229], v[102:105]
	v_mfma_f32_16x16x32_bf16 v[102:105], v[146:149], v[222:225], v[102:105]
	v_mfma_f32_16x16x32_bf16 v[86:89], v[146:149], v[230:233], v[86:89]
	v_mfma_f32_16x16x32_bf16 v[86:89], v[150:153], v[234:237], v[86:89]
	v_mfma_f32_16x16x32_bf16 v[82:85], v[210:213], v[234:237], v[82:85]
	v_mfma_f32_16x16x32_bf16 v[82:85], v[206:209], v[230:233], v[82:85]
	v_mfma_f32_16x16x32_bf16 v[66:69], v[206:209], v[238:241], v[66:69]
	v_mfma_f32_16x16x32_bf16 v[66:69], v[210:213], v[242:245], v[66:69]
	v_mfma_f32_16x16x32_bf16 v[70:73], v[150:153], v[242:245], v[70:73]
	v_mfma_f32_16x16x32_bf16 v[70:73], v[146:149], v[238:241], v[70:73]
	s_barrier
	s_add_i32 s68, s76, s50
	v_lshl_add_u64 v[184:185], s[66:67], 0, v[0:1]
	s_mov_b32 m0, s68
	ds_read_b128 v[214:217], v188 offset:16384
	ds_read_b128 v[218:221], v188 offset:17408
	ds_read_b128 v[222:225], v188 offset:18432
	ds_read_b128 v[226:229], v188 offset:19456
	ds_read_b128 v[230:233], v188 offset:20480
	ds_read_b128 v[234:237], v188 offset:21504
	ds_read_b128 v[238:241], v188 offset:22528
	ds_read_b128 v[242:245], v188 offset:23552
	global_load_lds_dwordx4 v[184:185], off
	s_add_i32 m0, s68, 0x2000
	v_lshl_add_u64 v[190:191], s[66:67], 0, v[164:165]
	s_add_u32 s66, s66, s12
	s_addc_u32 s67, s67, 0
	s_add_i32 s65, s65, s50
	global_load_lds_dwordx4 v[190:191], off
	v_lshl_add_u64 v[246:247], s[66:67], 0, v[0:1]
	s_mov_b32 m0, s65
	v_lshl_add_u64 v[248:249], s[66:67], 0, v[164:165]
	global_load_lds_dwordx4 v[246:247], off
	s_add_i32 m0, s65, 0x2000
	v_lshl_add_u64 v[250:251], s[26:27], 0, v[160:161]
	global_load_lds_dwordx4 v[248:249], off
	s_mov_b32 m0, s51
	s_nop 0
	global_load_lds_dwordx4 v[250:251], off
	v_lshl_add_u64 v[250:251], s[26:27], 0, v[162:163]
	s_mov_b32 m0, s52
	s_nop 0
	global_load_lds_dwordx4 v[250:251], off
	s_waitcnt vmcnt(8)
	.p2align 3
	s_waitcnt lgkmcnt(0)
	s_barrier
	v_mfma_f32_16x16x32_bf16 v[62:65], v[130:133], v[214:217], v[62:65]
	v_mfma_f32_16x16x32_bf16 v[62:65], v[134:137], v[218:221], v[62:65]
	v_mfma_f32_16x16x32_bf16 v[58:61], v[142:145], v[218:221], v[58:61]
	v_mfma_f32_16x16x32_bf16 v[58:61], v[138:141], v[214:217], v[58:61]
	v_mfma_f32_16x16x32_bf16 v[42:45], v[138:141], v[222:225], v[42:45]
	v_mfma_f32_16x16x32_bf16 v[42:45], v[142:145], v[226:229], v[42:45]
	v_mfma_f32_16x16x32_bf16 v[46:49], v[134:137], v[226:229], v[46:49]
	v_mfma_f32_16x16x32_bf16 v[46:49], v[130:133], v[222:225], v[46:49]
	v_mfma_f32_16x16x32_bf16 v[30:33], v[130:133], v[230:233], v[30:33]
	v_mfma_f32_16x16x32_bf16 v[30:33], v[134:137], v[234:237], v[30:33]
	v_mfma_f32_16x16x32_bf16 v[26:29], v[142:145], v[234:237], v[26:29]
	v_mfma_f32_16x16x32_bf16 v[26:29], v[138:141], v[230:233], v[26:29]
	v_mfma_f32_16x16x32_bf16 v[10:13], v[138:141], v[238:241], v[10:13]
	v_mfma_f32_16x16x32_bf16 v[10:13], v[142:145], v[242:245], v[10:13]
	v_mfma_f32_16x16x32_bf16 v[14:17], v[134:137], v[242:245], v[14:17]
	v_mfma_f32_16x16x32_bf16 v[14:17], v[130:133], v[238:241], v[14:17]
	v_mfma_f32_16x16x32_bf16 v[54:57], v[146:149], v[214:217], v[54:57]
	v_mfma_f32_16x16x32_bf16 v[54:57], v[150:153], v[218:221], v[54:57]
	v_mfma_f32_16x16x32_bf16 v[50:53], v[210:213], v[218:221], v[50:53]
	v_mfma_f32_16x16x32_bf16 v[50:53], v[206:209], v[214:217], v[50:53]
	v_mfma_f32_16x16x32_bf16 v[34:37], v[206:209], v[222:225], v[34:37]
	v_mfma_f32_16x16x32_bf16 v[34:37], v[210:213], v[226:229], v[34:37]
	v_mfma_f32_16x16x32_bf16 v[38:41], v[150:153], v[226:229], v[38:41]
	v_mfma_f32_16x16x32_bf16 v[38:41], v[146:149], v[222:225], v[38:41]
	v_mfma_f32_16x16x32_bf16 v[22:25], v[146:149], v[230:233], v[22:25]
	v_mfma_f32_16x16x32_bf16 v[22:25], v[150:153], v[234:237], v[22:25]
	v_mfma_f32_16x16x32_bf16 v[18:21], v[210:213], v[234:237], v[18:21]
	v_mfma_f32_16x16x32_bf16 v[18:21], v[206:209], v[230:233], v[18:21]
	v_mfma_f32_16x16x32_bf16 v[2:5], v[206:209], v[238:241], v[2:5]
	v_mfma_f32_16x16x32_bf16 v[2:5], v[210:213], v[242:245], v[2:5]
	v_mfma_f32_16x16x32_bf16 v[6:9], v[150:153], v[242:245], v[6:9]
	v_mfma_f32_16x16x32_bf16 v[6:9], v[146:149], v[238:241], v[6:9]
	s_barrier
; #define PG8_STAGE(bufoff, gbase, voff) do { _Pragma("unroll") for (int _i = 0; _i < 2; ++_i) \
;         __builtin_amdgcn_global_load_lds((const unsigned*)((const char*)(gbase) + (voff)[_i]), (PG8_LAS unsigned*)(lds + (bufoff) + ldsw + _i * 8192), 16, 0, 0); } while (0)
; #define PG8_LDA(dst, b, h) do { _Pragma("unroll") for (int m = 0; m < 4; ++m) _Pragma("unroll") for (int k = 0; k < 2; ++k) dst[m][k] = *(const PG8_LAS bf16x8*)(lds + PG8_SA(b, h) + aoff + m * 2048 + k * 1024); } while (0)
; #define PG8_LDB(dst, b, h) do { _Pragma("unroll") for (int n = 0; n < 2; ++n) _Pragma("unroll") for (int k = 0; k < 2; ++k) dst[n][k] = *(const PG8_LAS bf16x8*)(lds + PG8_SB(b, h) + boff + n * 2048 + k * 1024); } while (0)
; #define PG8_MMA(ai, bj, At, Bt) do { __builtin_amdgcn_s_setprio(1); _Pragma("unroll") for (int m = 0; m < 4; ++m) _Pragma("unroll") for (int n = 0; n < 2; ++n) _Pragma("unroll") for (int k = 0; k < 2; ++k) \
;         acc[ai][bj][m][n] = __builtin_amdgcn_mfma_f32_16x16x32_bf16(Bt[n][k], At[m][k], acc[ai][bj][m][n], 0, 0, 0); __builtin_amdgcn_s_setprio(0); } while (0)
; #define PG8_WAIT_V(n) asm volatile("s_waitcnt vmcnt(" #n ")" ::: "memory")
; #define PG8_WAIT_L(n) asm volatile("s_waitcnt lgkmcnt(" #n ")" ::: "memory")
; #define PG8_BAR __builtin_amdgcn_s_barrier()
; #define PG8_SCHED __builtin_amdgcn_sched_barrier(0)
; template <class Epi, class Sched, bool ALIGN_EPI = false, bool SP2 = false>
; __device__ __forceinline__ void gemm_phase(PG8_LAS unsigned char* lds, const Gemm g, const Sched& S, const Epi& E) {
;     ...
;             PG8_LDB(B0, 1, 0); PG8_LDB(B1, 1, 1); PG8_SCHED; PG8_LDA(At, 1, 0); PG8_STAGE(PG8_SA(0, 1), a2 + hstep, voffA);
;             PG8_WAIT_V(8); PG8_WAIT_L(0); PG8_BAR; PG8_MMA(0, 0, At, B0); PG8_MMA(0, 1, At, B1); PG8_BAR; PG8_SCHED;
;             PG8_LDA(At, 1, 1); PG8_STAGE(PG8_SB(1, 0), b3, voffB); PG8_STAGE(PG8_SB(1, 1), b3 + hstep, voffB); PG8_STAGE(PG8_SA(1, 0), a3, voffA);
;             PG8_WAIT_V(8); PG8_WAIT_L(0); PG8_BAR; PG8_MMA(1, 0, At, B0); PG8_MMA(1, 1, At, B1); PG8_BAR; PG8_SCHED;
	s_add_i32 s65, 0, 0x18000
	s_add_i32 s66, 0, 0x1c000
	v_add_u32_e32 v142, s65, v187
	v_add_u32_e32 v167, s66, v187
	ds_read_b128 v[130:133], v142
	ds_read_b128 v[134:137], v142 offset:1024
	ds_read_b128 v[138:141], v142 offset:2048
	ds_read_b128 v[142:145], v142 offset:3072
	ds_read_b128 v[146:149], v167
	ds_read_b128 v[150:153], v167 offset:1024
	ds_read_b128 v[206:209], v167 offset:2048
	ds_read_b128 v[210:213], v167 offset:3072
	s_add_u32 s26, s26, s12
	s_addc_u32 s27, s27, 0
	s_mov_b32 m0, s53
	v_lshl_add_u64 v[250:251], s[26:27], 0, v[160:161]
	ds_read_b128 v[214:217], v188 offset:32768
	ds_read_b128 v[218:221], v188 offset:33792
	ds_read_b128 v[222:225], v188 offset:34816
	ds_read_b128 v[226:229], v188 offset:35840
	ds_read_b128 v[230:233], v188 offset:36864
	ds_read_b128 v[234:237], v188 offset:37888
	ds_read_b128 v[238:241], v188 offset:38912
	ds_read_b128 v[242:245], v188 offset:39936
	global_load_lds_dwordx4 v[250:251], off
	v_lshl_add_u64 v[250:251], s[26:27], 0, v[162:163]
	s_mov_b32 m0, s54
	s_nop 0
	global_load_lds_dwordx4 v[250:251], off
	s_waitcnt vmcnt(8)
	.p2align 3
	s_waitcnt lgkmcnt(0)
	s_barrier
	v_mfma_f32_16x16x32_bf16 v[126:129], v[130:133], v[214:217], v[126:129]
	v_mfma_f32_16x16x32_bf16 v[126:129], v[134:137], v[218:221], v[126:129]
	v_mfma_f32_16x16x32_bf16 v[122:125], v[142:145], v[218:221], v[122:125]
	v_mfma_f32_16x16x32_bf16 v[122:125], v[138:141], v[214:217], v[122:125]
	v_mfma_f32_16x16x32_bf16 v[106:109], v[138:141], v[222:225], v[106:109]
	v_mfma_f32_16x16x32_bf16 v[106:109], v[142:145], v[226:229], v[106:109]
	v_mfma_f32_16x16x32_bf16 v[110:113], v[134:137], v[226:229], v[110:113]
	v_mfma_f32_16x16x32_bf16 v[110:113], v[130:133], v[222:225], v[110:113]
	v_mfma_f32_16x16x32_bf16 v[94:97], v[130:133], v[230:233], v[94:97]
	v_mfma_f32_16x16x32_bf16 v[94:97], v[134:137], v[234:237], v[94:97]
	v_mfma_f32_16x16x32_bf16 v[90:93], v[142:145], v[234:237], v[90:93]
	v_mfma_f32_16x16x32_bf16 v[90:93], v[138:141], v[230:233], v[90:93]
	v_mfma_f32_16x16x32_bf16 v[74:77], v[138:141], v[238:241], v[74:77]
	v_mfma_f32_16x16x32_bf16 v[74:77], v[142:145], v[242:245], v[74:77]
	v_mfma_f32_16x16x32_bf16 v[78:81], v[134:137], v[242:245], v[78:81]
	v_mfma_f32_16x16x32_bf16 v[78:81], v[130:133], v[238:241], v[78:81]
	v_mfma_f32_16x16x32_bf16 v[118:121], v[146:149], v[214:217], v[118:121]
	v_mfma_f32_16x16x32_bf16 v[118:121], v[150:153], v[218:221], v[118:121]
	v_mfma_f32_16x16x32_bf16 v[114:117], v[210:213], v[218:221], v[114:117]
	v_mfma_f32_16x16x32_bf16 v[114:117], v[206:209], v[214:217], v[114:117]
	v_mfma_f32_16x16x32_bf16 v[98:101], v[206:209], v[222:225], v[98:101]
	v_mfma_f32_16x16x32_bf16 v[98:101], v[210:213], v[226:229], v[98:101]
	v_mfma_f32_16x16x32_bf16 v[102:105], v[150:153], v[226:229], v[102:105]
	v_mfma_f32_16x16x32_bf16 v[102:105], v[146:149], v[222:225], v[102:105]
	v_mfma_f32_16x16x32_bf16 v[86:89], v[146:149], v[230:233], v[86:89]
	v_mfma_f32_16x16x32_bf16 v[86:89], v[150:153], v[234:237], v[86:89]
	v_mfma_f32_16x16x32_bf16 v[82:85], v[210:213], v[234:237], v[82:85]
	v_mfma_f32_16x16x32_bf16 v[82:85], v[206:209], v[230:233], v[82:85]
	v_mfma_f32_16x16x32_bf16 v[66:69], v[206:209], v[238:241], v[66:69]
	v_mfma_f32_16x16x32_bf16 v[66:69], v[210:213], v[242:245], v[66:69]
	v_mfma_f32_16x16x32_bf16 v[70:73], v[150:153], v[242:245], v[70:73]
	v_mfma_f32_16x16x32_bf16 v[70:73], v[146:149], v[238:241], v[70:73]
	s_barrier
	s_add_i32 s26, s65, s50
	v_lshl_add_u64 v[184:185], v[184:185], 0, s[38:39]
	s_mov_b32 m0, s26
	ds_read_b128 v[214:217], v188 offset:49152
	ds_read_b128 v[218:221], v188 offset:50176
	ds_read_b128 v[222:225], v188 offset:51200
	ds_read_b128 v[226:229], v188 offset:52224
	ds_read_b128 v[230:233], v188 offset:53248
	ds_read_b128 v[234:237], v188 offset:54272
	ds_read_b128 v[238:241], v188 offset:55296
	ds_read_b128 v[242:245], v188 offset:56320
	global_load_lds_dwordx4 v[184:185], off
	v_lshl_add_u64 v[184:185], v[190:191], 0, s[38:39]
	s_add_i32 m0, s26, 0x2000
	s_add_i32 s26, s66, s50
	global_load_lds_dwordx4 v[184:185], off
	v_lshl_add_u64 v[184:185], v[246:247], 0, s[38:39]
	s_mov_b32 m0, s26
	s_nop 0
	global_load_lds_dwordx4 v[184:185], off
	v_lshl_add_u64 v[184:185], v[248:249], 0, s[38:39]
	s_add_i32 m0, s26, 0x2000
	s_nop 0
	global_load_lds_dwordx4 v[184:185], off
	v_lshl_add_u64 v[184:185], s[24:25], 0, v[160:161]
	s_mov_b32 m0, s56
	s_nop 0
	global_load_lds_dwordx4 v[184:185], off
	v_lshl_add_u64 v[184:185], s[24:25], 0, v[162:163]
	s_mov_b32 m0, s57
	s_nop 0
	global_load_lds_dwordx4 v[184:185], off
	s_waitcnt vmcnt(8)
	.p2align 3
	s_waitcnt lgkmcnt(0)
	s_barrier
	v_mfma_f32_16x16x32_bf16 v[62:65], v[130:133], v[214:217], v[62:65]
	v_mfma_f32_16x16x32_bf16 v[62:65], v[134:137], v[218:221], v[62:65]
	v_mfma_f32_16x16x32_bf16 v[58:61], v[142:145], v[218:221], v[58:61]
	v_mfma_f32_16x16x32_bf16 v[58:61], v[138:141], v[214:217], v[58:61]
	v_mfma_f32_16x16x32_bf16 v[42:45], v[138:141], v[222:225], v[42:45]
	v_mfma_f32_16x16x32_bf16 v[42:45], v[142:145], v[226:229], v[42:45]
	v_mfma_f32_16x16x32_bf16 v[46:49], v[134:137], v[226:229], v[46:49]
	v_mfma_f32_16x16x32_bf16 v[46:49], v[130:133], v[222:225], v[46:49]
	v_mfma_f32_16x16x32_bf16 v[30:33], v[130:133], v[230:233], v[30:33]
	v_mfma_f32_16x16x32_bf16 v[30:33], v[134:137], v[234:237], v[30:33]
	v_mfma_f32_16x16x32_bf16 v[26:29], v[142:145], v[234:237], v[26:29]
	v_mfma_f32_16x16x32_bf16 v[26:29], v[138:141], v[230:233], v[26:29]
	v_mfma_f32_16x16x32_bf16 v[10:13], v[138:141], v[238:241], v[10:13]
	v_mfma_f32_16x16x32_bf16 v[10:13], v[142:145], v[242:245], v[10:13]
	v_mfma_f32_16x16x32_bf16 v[14:17], v[134:137], v[242:245], v[14:17]
	v_mfma_f32_16x16x32_bf16 v[14:17], v[130:133], v[238:241], v[14:17]
	v_mfma_f32_16x16x32_bf16 v[54:57], v[146:149], v[214:217], v[54:57]
	v_mfma_f32_16x16x32_bf16 v[54:57], v[150:153], v[218:221], v[54:57]
	v_mfma_f32_16x16x32_bf16 v[50:53], v[210:213], v[218:221], v[50:53]
	v_mfma_f32_16x16x32_bf16 v[50:53], v[206:209], v[214:217], v[50:53]
	v_mfma_f32_16x16x32_bf16 v[34:37], v[206:209], v[222:225], v[34:37]
	v_mfma_f32_16x16x32_bf16 v[34:37], v[210:213], v[226:229], v[34:37]
	v_mfma_f32_16x16x32_bf16 v[38:41], v[150:153], v[226:229], v[38:41]
	v_mfma_f32_16x16x32_bf16 v[38:41], v[146:149], v[222:225], v[38:41]
	v_mfma_f32_16x16x32_bf16 v[22:25], v[146:149], v[230:233], v[22:25]
	v_mfma_f32_16x16x32_bf16 v[22:25], v[150:153], v[234:237], v[22:25]
	v_mfma_f32_16x16x32_bf16 v[18:21], v[210:213], v[234:237], v[18:21]
	v_mfma_f32_16x16x32_bf16 v[18:21], v[206:209], v[230:233], v[18:21]
	v_mfma_f32_16x16x32_bf16 v[2:5], v[206:209], v[238:241], v[2:5]
	v_mfma_f32_16x16x32_bf16 v[2:5], v[210:213], v[242:245], v[2:5]
	v_mfma_f32_16x16x32_bf16 v[6:9], v[150:153], v[242:245], v[6:9]
	v_mfma_f32_16x16x32_bf16 v[6:9], v[146:149], v[238:241], v[6:9]
	s_barrier
	s_add_u32 s47, s47, 0x100
	s_addc_u32 s48, s48, 0
	s_add_u32 s2, s2, 0x8000
	s_addc_u32 s3, s3, 0
	s_cmp_ge_u32 s49, s55
	s_mov_b32 s24, s49
	s_cbranch_scc0 .LBB0_310

; #define PG8_STAGE(bufoff, gbase, voff) do { _Pragma("unroll") for (int _i = 0; _i < 2; ++_i) \
;         __builtin_amdgcn_global_load_lds((const unsigned*)((const char*)(gbase) + (voff)[_i]), (PG8_LAS unsigned*)(lds + (bufoff) + ldsw + _i * 8192), 16, 0, 0); } while (0)
; #define PG8_LDA(dst, b, h) do { _Pragma("unroll") for (int m = 0; m < 4; ++m) _Pragma("unroll") for (int k = 0; k < 2; ++k) dst[m][k] = *(const PG8_LAS bf16x8*)(lds + PG8_SA(b, h) + aoff + m * 2048 + k * 1024); } while (0)
; #define PG8_LDB(dst, b, h) do { _Pragma("unroll") for (int n = 0; n < 2; ++n) _Pragma("unroll") for (int k = 0; k < 2; ++k) dst[n][k] = *(const PG8_LAS bf16x8*)(lds + PG8_SB(b, h) + boff + n * 2048 + k * 1024); } while (0)
; #define PG8_WAIT_V(n) asm volatile("s_waitcnt vmcnt(" #n ")" ::: "memory")
; #define PG8_WAIT_L(n) asm volatile("s_waitcnt lgkmcnt(" #n ")" ::: "memory")
; #define PG8_BAR __builtin_amdgcn_s_barrier()
; #define PG8_SCHED __builtin_amdgcn_sched_barrier(0)
; template <class Epi, class Sched, bool ALIGN_EPI = false, bool SP2 = false>
; __device__ __forceinline__ void gemm_phase(PG8_LAS unsigned char* lds, const Gemm g, const Sched& S, const Epi& E) {
;     ...
;         const bool has_next = S.next(ui + 1, nxt);
;         const char* nA = has_next ? (const char*)g.A + (size_t)nxt.pm * tstep : cA; const char* nB = has_next ? (const char*)g.Bt + (size_t)nxt.pn * tstep : cB;
;         for (int t = 0; t < nt; t += 2) {
;             const bool last = (t == nt - 2);
;             const char* a1 = cA + (size_t)(t + 1) * kstepA;
;             const char* a2 = last ? nA : cA + (size_t)(t + 2) * kstepA; const char* b2 = last ? nB : cB + (size_t)(t + 2) * kstep;
;             const char* a3 = a2 + kstepA; const char* b3 = b2 + kstep;
;             if (last && has_next) S.a_ready(nxt);
;             if constexpr (SP2) {
;             PG8_LDB(B0, 0, 0); PG8_LDB(B1, 0, 1); PG8_SCHED; PG8_LDA(At, 0, 0); PG8_STAGE(PG8_SA(1, 1), a1 + hstep, voffA);
;             PG8_WAIT_V(8); PG8_WAIT_L(0); PG8_BAR; PG8_MMA(0, 0, At, B0); PG8_MMA(0, 1, At, B1); PG8_BAR; PG8_SCHED;
;             PG8_LDA(At, 0, 1); PG8_STAGE(PG8_SB(0, 0), b2, voffB); PG8_STAGE(PG8_SB(0, 1), b2 + hstep, voffB); PG8_STAGE(PG8_SA(0, 0), a2, voffA);
;             PG8_WAIT_V(8); PG8_WAIT_L(0); PG8_BAR; PG8_MMA(1, 0, At, B0); PG8_MMA(1, 1, At, B1); PG8_BAR; PG8_SCHED;
.LBB0_408:
	s_ashr_i32 s11, s10, 31
	s_lshl_b64 s[12:13], s[10:11], 19
	s_add_u32 s12, s30, s12
	s_addc_u32 s13, s31, s13
	s_and_b64 s[18:19], s[4:5], exec
	s_cselect_b32 s11, s13, s23
	s_cselect_b32 s53, s12, s22
	s_ashr_i32 s9, s8, 31
	s_lshl_b64 s[18:19], s[8:9], 19
	s_add_u32 s18, s37, s18
	s_addc_u32 s19, s44, s19
	s_and_b64 s[26:27], s[4:5], exec
	s_cselect_b32 s9, s19, s25
	s_cselect_b32 s54, s18, s24
	s_add_u32 s55, s24, 0x100
	s_addc_u32 s56, s25, 0
	s_mov_b32 s57, -2
	s_add_u32 s24, s22, 0x8000
	s_addc_u32 s25, s23, 0
	s_cmp_eq_u32 s57, 12
	s_cselect_b32 s42, s53, s24
	s_cselect_b32 s43, s11, s25
	s_cselect_b32 s40, s54, s55
	s_cselect_b32 s41, s9, s56
	s_add_u32 s26, s42, 0x4000
	s_addc_u32 s27, s43, 0
	v_add_u32_e32 v145, s76, v142
	s_add_i32 s58, 0, 0x14000
	ds_read_b128 v[146:149], v145
	ds_read_b128 v[150:153], v145 offset:1024
	ds_read_b128 v[160:163], v145 offset:2048
	ds_read_b128 v[164:167], v145 offset:3072
	v_add_u32_e32 v145, s58, v142
	ds_read_b128 v[168:171], v145
	ds_read_b128 v[172:175], v145 offset:1024
	ds_read_b128 v[176:179], v145 offset:2048
	ds_read_b128 v[180:183], v145 offset:3072
	v_lshl_add_u64 v[230:231], s[22:23], 0, v[140:141]
	s_add_i32 m0, s45, 0xc000
	ds_read_b128 v[184:187], v144
	ds_read_b128 v[188:191], v144 offset:1024
	ds_read_b128 v[206:209], v144 offset:2048
	ds_read_b128 v[210:213], v144 offset:3072
	ds_read_b128 v[214:217], v144 offset:4096
	ds_read_b128 v[218:221], v144 offset:5120
	ds_read_b128 v[222:225], v144 offset:6144
	ds_read_b128 v[226:229], v144 offset:7168
	global_load_lds_dwordx4 v[230:231], off
	v_lshl_add_u64 v[230:231], s[22:23], 0, v[138:139]
	s_add_i32 m0, s45, 0xe000
	s_nop 0
	global_load_lds_dwordx4 v[230:231], off
	s_waitcnt vmcnt(8)
	.p2align 3
	s_waitcnt lgkmcnt(0)
	s_barrier
	v_mfma_f32_16x16x32_bf16 v[126:129], v[146:149], v[184:187], 0
	v_mfma_f32_16x16x32_bf16 v[126:129], v[150:153], v[188:191], v[126:129]
	v_mfma_f32_16x16x32_bf16 v[118:121], v[164:167], v[188:191], 0
	v_mfma_f32_16x16x32_bf16 v[118:121], v[160:163], v[184:187], v[118:121]
	v_mfma_f32_16x16x32_bf16 v[102:105], v[160:163], v[206:209], 0
	v_mfma_f32_16x16x32_bf16 v[102:105], v[164:167], v[210:213], v[102:105]
	v_mfma_f32_16x16x32_bf16 v[110:113], v[150:153], v[210:213], 0
	v_mfma_f32_16x16x32_bf16 v[110:113], v[146:149], v[206:209], v[110:113]
	v_mfma_f32_16x16x32_bf16 v[94:97], v[146:149], v[214:217], 0
	v_mfma_f32_16x16x32_bf16 v[94:97], v[150:153], v[218:221], v[94:97]
	v_mfma_f32_16x16x32_bf16 v[86:89], v[164:167], v[218:221], 0
	v_mfma_f32_16x16x32_bf16 v[86:89], v[160:163], v[214:217], v[86:89]
	v_mfma_f32_16x16x32_bf16 v[70:73], v[160:163], v[222:225], 0
	v_mfma_f32_16x16x32_bf16 v[70:73], v[164:167], v[226:229], v[70:73]
	v_mfma_f32_16x16x32_bf16 v[78:81], v[150:153], v[226:229], 0
	v_mfma_f32_16x16x32_bf16 v[78:81], v[146:149], v[222:225], v[78:81]
	v_mfma_f32_16x16x32_bf16 v[122:125], v[168:171], v[184:187], 0
	v_mfma_f32_16x16x32_bf16 v[122:125], v[172:175], v[188:191], v[122:125]
	v_mfma_f32_16x16x32_bf16 v[114:117], v[180:183], v[188:191], 0
	v_mfma_f32_16x16x32_bf16 v[114:117], v[176:179], v[184:187], v[114:117]
	v_mfma_f32_16x16x32_bf16 v[98:101], v[176:179], v[206:209], 0
	v_mfma_f32_16x16x32_bf16 v[98:101], v[180:183], v[210:213], v[98:101]
	v_mfma_f32_16x16x32_bf16 v[106:109], v[172:175], v[210:213], 0
	v_mfma_f32_16x16x32_bf16 v[106:109], v[168:171], v[206:209], v[106:109]
	v_mfma_f32_16x16x32_bf16 v[90:93], v[168:171], v[214:217], 0
	v_mfma_f32_16x16x32_bf16 v[90:93], v[172:175], v[218:221], v[90:93]
	v_mfma_f32_16x16x32_bf16 v[82:85], v[180:183], v[218:221], 0
	v_mfma_f32_16x16x32_bf16 v[82:85], v[176:179], v[214:217], v[82:85]
	v_mfma_f32_16x16x32_bf16 v[66:69], v[176:179], v[222:225], 0
	v_mfma_f32_16x16x32_bf16 v[66:69], v[180:183], v[226:229], v[66:69]
	v_mfma_f32_16x16x32_bf16 v[74:77], v[172:175], v[226:229], 0
	v_mfma_f32_16x16x32_bf16 v[74:77], v[168:171], v[222:225], v[74:77]
	s_barrier
	s_add_i32 s22, s76, s29
	v_lshl_add_u64 v[230:231], s[40:41], 0, v[0:1]
	s_mov_b32 m0, s22
	ds_read_b128 v[184:187], v144 offset:16384
	ds_read_b128 v[188:191], v144 offset:17408
	ds_read_b128 v[206:209], v144 offset:18432
	ds_read_b128 v[210:213], v144 offset:19456
	ds_read_b128 v[214:217], v144 offset:20480
	ds_read_b128 v[218:221], v144 offset:21504
	ds_read_b128 v[222:225], v144 offset:22528
	ds_read_b128 v[226:229], v144 offset:23552
	global_load_lds_dwordx4 v[230:231], off
	s_add_i32 m0, s22, 0x2000
	s_add_u32 s22, s40, 0x40000
	v_lshl_add_u64 v[232:233], s[40:41], 0, v[130:131]
	s_addc_u32 s23, s41, 0
	s_add_i32 s58, s58, s29
	global_load_lds_dwordx4 v[232:233], off
	v_lshl_add_u64 v[234:235], s[22:23], 0, v[0:1]
	s_mov_b32 m0, s58
	s_nop 0
	global_load_lds_dwordx4 v[234:235], off
	v_lshl_add_u64 v[234:235], s[22:23], 0, v[130:131]
	s_add_i32 m0, s58, 0x2000
	s_nop 0
	global_load_lds_dwordx4 v[234:235], off
	v_lshl_add_u64 v[234:235], s[42:43], 0, v[134:135]
	s_mov_b32 m0, s45
	s_nop 0
	global_load_lds_dwordx4 v[234:235], off
	v_lshl_add_u64 v[234:235], s[42:43], 0, v[132:133]
	s_mov_b32 m0, s46
	s_nop 0
	global_load_lds_dwordx4 v[234:235], off
	s_waitcnt vmcnt(8)
	.p2align 3
	s_waitcnt lgkmcnt(0)
	s_barrier
; #define PG8_STAGE(bufoff, gbase, voff) do { _Pragma("unroll") for (int _i = 0; _i < 2; ++_i) \
;         __builtin_amdgcn_global_load_lds((const unsigned*)((const char*)(gbase) + (voff)[_i]), (PG8_LAS unsigned*)(lds + (bufoff) + ldsw + _i * 8192), 16, 0, 0); } while (0)
; #define PG8_LDA(dst, b, h) do { _Pragma("unroll") for (int m = 0; m < 4; ++m) _Pragma("unroll") for (int k = 0; k < 2; ++k) dst[m][k] = *(const PG8_LAS bf16x8*)(lds + PG8_SA(b, h) + aoff + m * 2048 + k * 1024); } while (0)
; #define PG8_LDB(dst, b, h) do { _Pragma("unroll") for (int n = 0; n < 2; ++n) _Pragma("unroll") for (int k = 0; k < 2; ++k) dst[n][k] = *(const PG8_LAS bf16x8*)(lds + PG8_SB(b, h) + boff + n * 2048 + k * 1024); } while (0)
; #define PG8_MMA(ai, bj, At, Bt) do { __builtin_amdgcn_s_setprio(1); _Pragma("unroll") for (int m = 0; m < 4; ++m) _Pragma("unroll") for (int n = 0; n < 2; ++n) _Pragma("unroll") for (int k = 0; k < 2; ++k) \
;         acc[ai][bj][m][n] = __builtin_amdgcn_mfma_f32_16x16x32_bf16(Bt[n][k], At[m][k], acc[ai][bj][m][n], 0, 0, 0); __builtin_amdgcn_s_setprio(0); } while (0)
; #define PG8_WAIT_V(n) asm volatile("s_waitcnt vmcnt(" #n ")" ::: "memory")
; #define PG8_WAIT_L(n) asm volatile("s_waitcnt lgkmcnt(" #n ")" ::: "memory")
; #define PG8_BAR __builtin_amdgcn_s_barrier()
; #define PG8_SCHED __builtin_amdgcn_sched_barrier(0)
; template <class Epi, class Sched, bool ALIGN_EPI = false, bool SP2 = false>
; __device__ __forceinline__ void gemm_phase(PG8_LAS unsigned char* lds, const Gemm g, const Sched& S, const Epi& E) {
;     ...
;             PG8_WAIT_V(8); PG8_WAIT_L(0); PG8_BAR; PG8_MMA(1, 0, At, B0); PG8_MMA(1, 1, At, B1); PG8_BAR; PG8_SCHED;
;             PG8_LDB(B0, 1, 0); PG8_LDB(B1, 1, 1); PG8_SCHED; PG8_LDA(At, 1, 0); PG8_STAGE(PG8_SA(0, 1), a2 + hstep, voffA);
;             PG8_WAIT_V(8); PG8_WAIT_L(0); PG8_BAR; PG8_MMA(0, 0, At, B0); PG8_MMA(0, 1, At, B1); PG8_BAR; PG8_SCHED;
	v_mfma_f32_16x16x32_bf16 v[62:65], v[146:149], v[184:187], 0
	v_mfma_f32_16x16x32_bf16 v[62:65], v[150:153], v[188:191], v[62:65]
	v_mfma_f32_16x16x32_bf16 v[54:57], v[164:167], v[188:191], 0
	v_mfma_f32_16x16x32_bf16 v[54:57], v[160:163], v[184:187], v[54:57]
	v_mfma_f32_16x16x32_bf16 v[38:41], v[160:163], v[206:209], 0
	v_mfma_f32_16x16x32_bf16 v[38:41], v[164:167], v[210:213], v[38:41]
	v_mfma_f32_16x16x32_bf16 v[46:49], v[150:153], v[210:213], 0
	v_mfma_f32_16x16x32_bf16 v[46:49], v[146:149], v[206:209], v[46:49]
	v_mfma_f32_16x16x32_bf16 v[30:33], v[146:149], v[214:217], 0
	v_mfma_f32_16x16x32_bf16 v[30:33], v[150:153], v[218:221], v[30:33]
	v_mfma_f32_16x16x32_bf16 v[22:25], v[164:167], v[218:221], 0
	v_mfma_f32_16x16x32_bf16 v[22:25], v[160:163], v[214:217], v[22:25]
	v_mfma_f32_16x16x32_bf16 v[6:9], v[160:163], v[222:225], 0
	v_mfma_f32_16x16x32_bf16 v[6:9], v[164:167], v[226:229], v[6:9]
	v_mfma_f32_16x16x32_bf16 v[14:17], v[150:153], v[226:229], 0
	v_mfma_f32_16x16x32_bf16 v[14:17], v[146:149], v[222:225], v[14:17]
	v_mfma_f32_16x16x32_bf16 v[58:61], v[168:171], v[184:187], 0
	v_mfma_f32_16x16x32_bf16 v[58:61], v[172:175], v[188:191], v[58:61]
	v_mfma_f32_16x16x32_bf16 v[50:53], v[180:183], v[188:191], 0
	v_mfma_f32_16x16x32_bf16 v[50:53], v[176:179], v[184:187], v[50:53]
	v_mfma_f32_16x16x32_bf16 v[34:37], v[176:179], v[206:209], 0
	v_mfma_f32_16x16x32_bf16 v[34:37], v[180:183], v[210:213], v[34:37]
	v_mfma_f32_16x16x32_bf16 v[42:45], v[172:175], v[210:213], 0
	v_mfma_f32_16x16x32_bf16 v[42:45], v[168:171], v[206:209], v[42:45]
	v_mfma_f32_16x16x32_bf16 v[26:29], v[168:171], v[214:217], 0
	v_mfma_f32_16x16x32_bf16 v[26:29], v[172:175], v[218:221], v[26:29]
	v_mfma_f32_16x16x32_bf16 v[18:21], v[180:183], v[218:221], 0
	v_mfma_f32_16x16x32_bf16 v[18:21], v[176:179], v[214:217], v[18:21]
	v_mfma_f32_16x16x32_bf16 v[2:5], v[176:179], v[222:225], 0
	v_mfma_f32_16x16x32_bf16 v[2:5], v[180:183], v[226:229], v[2:5]
	v_mfma_f32_16x16x32_bf16 v[10:13], v[172:175], v[226:229], 0
	v_mfma_f32_16x16x32_bf16 v[10:13], v[168:171], v[222:225], v[10:13]
	s_barrier
	s_add_i32 s58, 0, 0x18000
	v_add_u32_e32 v145, s58, v142
	s_add_i32 s59, 0, 0x1c000
	ds_read_b128 v[146:149], v145
	ds_read_b128 v[150:153], v145 offset:1024
	ds_read_b128 v[160:163], v145 offset:2048
	ds_read_b128 v[164:167], v145 offset:3072
	v_add_u32_e32 v145, s59, v142
	ds_read_b128 v[168:171], v145
	ds_read_b128 v[172:175], v145 offset:1024
	ds_read_b128 v[176:179], v145 offset:2048
	ds_read_b128 v[180:183], v145 offset:3072
	s_add_u32 s22, s42, 0x40000
	s_addc_u32 s23, s43, 0
	s_mov_b32 m0, s47
	v_lshl_add_u64 v[234:235], s[22:23], 0, v[134:135]
	ds_read_b128 v[184:187], v144 offset:32768
	ds_read_b128 v[188:191], v144 offset:33792
	ds_read_b128 v[206:209], v144 offset:34816
	ds_read_b128 v[210:213], v144 offset:35840
	ds_read_b128 v[214:217], v144 offset:36864
	ds_read_b128 v[218:221], v144 offset:37888
	ds_read_b128 v[222:225], v144 offset:38912
	ds_read_b128 v[226:229], v144 offset:39936
	global_load_lds_dwordx4 v[234:235], off
	v_lshl_add_u64 v[234:235], s[22:23], 0, v[132:133]
	s_mov_b32 m0, s48
	s_nop 0
	global_load_lds_dwordx4 v[234:235], off
	s_waitcnt vmcnt(8)
	.p2align 3
	s_waitcnt lgkmcnt(0)
	s_barrier
	v_mfma_f32_16x16x32_bf16 v[126:129], v[146:149], v[184:187], v[126:129]
	v_mfma_f32_16x16x32_bf16 v[126:129], v[150:153], v[188:191], v[126:129]
	v_mfma_f32_16x16x32_bf16 v[118:121], v[164:167], v[188:191], v[118:121]
	v_mfma_f32_16x16x32_bf16 v[118:121], v[160:163], v[184:187], v[118:121]
	v_mfma_f32_16x16x32_bf16 v[102:105], v[160:163], v[206:209], v[102:105]
	v_mfma_f32_16x16x32_bf16 v[102:105], v[164:167], v[210:213], v[102:105]
	v_mfma_f32_16x16x32_bf16 v[110:113], v[150:153], v[210:213], v[110:113]
	v_mfma_f32_16x16x32_bf16 v[110:113], v[146:149], v[206:209], v[110:113]
	v_mfma_f32_16x16x32_bf16 v[94:97], v[146:149], v[214:217], v[94:97]
	v_mfma_f32_16x16x32_bf16 v[94:97], v[150:153], v[218:221], v[94:97]
	v_mfma_f32_16x16x32_bf16 v[86:89], v[164:167], v[218:221], v[86:89]
	v_mfma_f32_16x16x32_bf16 v[86:89], v[160:163], v[214:217], v[86:89]
	v_mfma_f32_16x16x32_bf16 v[70:73], v[160:163], v[222:225], v[70:73]
	v_mfma_f32_16x16x32_bf16 v[70:73], v[164:167], v[226:229], v[70:73]
	v_mfma_f32_16x16x32_bf16 v[78:81], v[150:153], v[226:229], v[78:81]
	v_mfma_f32_16x16x32_bf16 v[78:81], v[146:149], v[222:225], v[78:81]
	v_mfma_f32_16x16x32_bf16 v[122:125], v[168:171], v[184:187], v[122:125]
	v_mfma_f32_16x16x32_bf16 v[122:125], v[172:175], v[188:191], v[122:125]
	v_mfma_f32_16x16x32_bf16 v[114:117], v[180:183], v[188:191], v[114:117]
	v_mfma_f32_16x16x32_bf16 v[114:117], v[176:179], v[184:187], v[114:117]
	v_mfma_f32_16x16x32_bf16 v[98:101], v[176:179], v[206:209], v[98:101]
	v_mfma_f32_16x16x32_bf16 v[98:101], v[180:183], v[210:213], v[98:101]
	v_mfma_f32_16x16x32_bf16 v[106:109], v[172:175], v[210:213], v[106:109]
	v_mfma_f32_16x16x32_bf16 v[106:109], v[168:171], v[206:209], v[106:109]
	v_mfma_f32_16x16x32_bf16 v[90:93], v[168:171], v[214:217], v[90:93]
	v_mfma_f32_16x16x32_bf16 v[90:93], v[172:175], v[218:221], v[90:93]
	v_mfma_f32_16x16x32_bf16 v[82:85], v[180:183], v[218:221], v[82:85]
	v_mfma_f32_16x16x32_bf16 v[82:85], v[176:179], v[214:217], v[82:85]
	v_mfma_f32_16x16x32_bf16 v[66:69], v[176:179], v[222:225], v[66:69]
	v_mfma_f32_16x16x32_bf16 v[66:69], v[180:183], v[226:229], v[66:69]
	v_mfma_f32_16x16x32_bf16 v[74:77], v[172:175], v[226:229], v[74:77]
	v_mfma_f32_16x16x32_bf16 v[74:77], v[168:171], v[222:225], v[74:77]
	s_barrier
; #define PG8_STAGE(bufoff, gbase, voff) do { _Pragma("unroll") for (int _i = 0; _i < 2; ++_i) \
;         __builtin_amdgcn_global_load_lds((const unsigned*)((const char*)(gbase) + (voff)[_i]), (PG8_LAS unsigned*)(lds + (bufoff) + ldsw + _i * 8192), 16, 0, 0); } while (0)
; #define PG8_LDA(dst, b, h) do { _Pragma("unroll") for (int m = 0; m < 4; ++m) _Pragma("unroll") for (int k = 0; k < 2; ++k) dst[m][k] = *(const PG8_LAS bf16x8*)(lds + PG8_SA(b, h) + aoff + m * 2048 + k * 1024); } while (0)
; #define PG8_LDB(dst, b, h) do { _Pragma("unroll") for (int n = 0; n < 2; ++n) _Pragma("unroll") for (int k = 0; k < 2; ++k) dst[n][k] = *(const PG8_LAS bf16x8*)(lds + PG8_SB(b, h) + boff + n * 2048 + k * 1024); } while (0)
; template <class Epi, class Sched, bool ALIGN_EPI = false, bool SP2 = false>
; __device__ __forceinline__ void gemm_phase(PG8_LAS unsigned char* lds, const Gemm g, const Sched& S, const Epi& E) {
;     ...
;         for (int t = 0; t < nt; t += 2) {
;             const bool last = (t == nt - 2);
;             const char* a1 = cA + (size_t)(t + 1) * kstepA;
;             const char* a2 = last ? nA : cA + (size_t)(t + 2) * kstepA; const char* b2 = last ? nB : cB + (size_t)(t + 2) * kstep;
;             const char* a3 = a2 + kstepA; const char* b3 = b2 + kstep;
;             if (last && has_next) S.a_ready(nxt);
;             if constexpr (SP2) {
;             PG8_LDB(B0, 0, 0); PG8_LDB(B1, 0, 1); PG8_SCHED; PG8_LDA(At, 0, 0); PG8_STAGE(PG8_SA(1, 1), a1 + hstep, voffA);
;             PG8_WAIT_V(8); PG8_WAIT_L(0); PG8_BAR; PG8_MMA(0, 0, At, B0); PG8_MMA(0, 1, At, B1); PG8_BAR; PG8_SCHED;
;             PG8_LDA(At, 0, 1); PG8_STAGE(PG8_SB(0, 0), b2, voffB); PG8_STAGE(PG8_SB(0, 1), b2 + hstep, voffB); PG8_STAGE(PG8_SA(0, 0), a2, voffA);
;             PG8_WAIT_V(8); PG8_WAIT_L(0); PG8_BAR; PG8_MMA(1, 0, At, B0); PG8_MMA(1, 1, At, B1); PG8_BAR; PG8_SCHED;
;             PG8_LDB(B0, 1, 0); PG8_LDB(B1, 1, 1); PG8_SCHED; PG8_LDA(At, 1, 0); PG8_STAGE(PG8_SA(0, 1), a2 + hstep, voffA);
;             PG8_WAIT_V(8); PG8_WAIT_L(0); PG8_BAR; PG8_MMA(0, 0, At, B0); PG8_MMA(0, 1, At, B1); PG8_BAR; PG8_SCHED;
;             PG8_LDA(At, 1, 1); PG8_STAGE(PG8_SB(1, 0), b3, voffB); PG8_STAGE(PG8_SB(1, 1), b3 + hstep, voffB); PG8_STAGE(PG8_SA(1, 0), a3, voffA);
;             PG8_WAIT_V(8); PG8_WAIT_L(0); PG8_BAR; PG8_MMA(1, 0, At, B0); PG8_MMA(1, 1, At, B1); PG8_BAR; PG8_SCHED;
	s_add_i32 s22, s58, s29
	v_lshl_add_u64 v[230:231], v[230:231], 0, s[38:39]
	s_mov_b32 m0, s22
	ds_read_b128 v[184:187], v144 offset:49152
	ds_read_b128 v[188:191], v144 offset:50176
	ds_read_b128 v[206:209], v144 offset:51200
	ds_read_b128 v[210:213], v144 offset:52224
	ds_read_b128 v[214:217], v144 offset:53248
	ds_read_b128 v[218:221], v144 offset:54272
	ds_read_b128 v[222:225], v144 offset:55296
	ds_read_b128 v[226:229], v144 offset:56320
	global_load_lds_dwordx4 v[230:231], off
	s_add_i32 m0, s22, 0x2000
	s_add_u32 s22, s40, 0x40080
	v_lshl_add_u64 v[230:231], v[232:233], 0, s[38:39]
	s_addc_u32 s23, s41, 0
	s_add_i32 s40, s59, s29
	global_load_lds_dwordx4 v[230:231], off
	v_lshl_add_u64 v[230:231], s[22:23], 0, v[0:1]
	s_mov_b32 m0, s40
	s_nop 0
	global_load_lds_dwordx4 v[230:231], off
	v_lshl_add_u64 v[230:231], s[22:23], 0, v[130:131]
	s_add_i32 m0, s40, 0x2000
	s_nop 0
	global_load_lds_dwordx4 v[230:231], off
	v_lshl_add_u64 v[230:231], s[26:27], 0, v[134:135]
	s_mov_b32 m0, s49
	s_nop 0
	global_load_lds_dwordx4 v[230:231], off
	v_lshl_add_u64 v[230:231], s[26:27], 0, v[132:133]
	s_mov_b32 m0, s50
	s_nop 0
	global_load_lds_dwordx4 v[230:231], off
	s_waitcnt vmcnt(8)
	.p2align 3
	s_waitcnt lgkmcnt(0)
	s_barrier
	v_mfma_f32_16x16x32_bf16 v[62:65], v[146:149], v[184:187], v[62:65]
	v_mfma_f32_16x16x32_bf16 v[62:65], v[150:153], v[188:191], v[62:65]
	v_mfma_f32_16x16x32_bf16 v[54:57], v[164:167], v[188:191], v[54:57]
	v_mfma_f32_16x16x32_bf16 v[54:57], v[160:163], v[184:187], v[54:57]
	v_mfma_f32_16x16x32_bf16 v[38:41], v[160:163], v[206:209], v[38:41]
	v_mfma_f32_16x16x32_bf16 v[38:41], v[164:167], v[210:213], v[38:41]
	v_mfma_f32_16x16x32_bf16 v[46:49], v[150:153], v[210:213], v[46:49]
	v_mfma_f32_16x16x32_bf16 v[46:49], v[146:149], v[206:209], v[46:49]
	v_mfma_f32_16x16x32_bf16 v[30:33], v[146:149], v[214:217], v[30:33]
	v_mfma_f32_16x16x32_bf16 v[30:33], v[150:153], v[218:221], v[30:33]
	v_mfma_f32_16x16x32_bf16 v[22:25], v[164:167], v[218:221], v[22:25]
	v_mfma_f32_16x16x32_bf16 v[22:25], v[160:163], v[214:217], v[22:25]
	v_mfma_f32_16x16x32_bf16 v[6:9], v[160:163], v[222:225], v[6:9]
	v_mfma_f32_16x16x32_bf16 v[6:9], v[164:167], v[226:229], v[6:9]
	v_mfma_f32_16x16x32_bf16 v[14:17], v[150:153], v[226:229], v[14:17]
	v_mfma_f32_16x16x32_bf16 v[14:17], v[146:149], v[222:225], v[14:17]
	v_mfma_f32_16x16x32_bf16 v[58:61], v[168:171], v[184:187], v[58:61]
	v_mfma_f32_16x16x32_bf16 v[58:61], v[172:175], v[188:191], v[58:61]
	v_mfma_f32_16x16x32_bf16 v[50:53], v[180:183], v[188:191], v[50:53]
	v_mfma_f32_16x16x32_bf16 v[50:53], v[176:179], v[184:187], v[50:53]
	v_mfma_f32_16x16x32_bf16 v[34:37], v[176:179], v[206:209], v[34:37]
	v_mfma_f32_16x16x32_bf16 v[34:37], v[180:183], v[210:213], v[34:37]
	v_mfma_f32_16x16x32_bf16 v[42:45], v[172:175], v[210:213], v[42:45]
	v_mfma_f32_16x16x32_bf16 v[42:45], v[168:171], v[206:209], v[42:45]
	v_mfma_f32_16x16x32_bf16 v[26:29], v[168:171], v[214:217], v[26:29]
	v_mfma_f32_16x16x32_bf16 v[26:29], v[172:175], v[218:221], v[26:29]
	v_mfma_f32_16x16x32_bf16 v[18:21], v[180:183], v[218:221], v[18:21]
	v_mfma_f32_16x16x32_bf16 v[18:21], v[176:179], v[214:217], v[18:21]
	v_mfma_f32_16x16x32_bf16 v[2:5], v[176:179], v[222:225], v[2:5]
	v_mfma_f32_16x16x32_bf16 v[2:5], v[180:183], v[226:229], v[2:5]
	v_mfma_f32_16x16x32_bf16 v[10:13], v[172:175], v[226:229], v[10:13]
	v_mfma_f32_16x16x32_bf16 v[10:13], v[168:171], v[222:225], v[10:13]
	s_barrier
	s_add_i32 s57, s57, 2
	s_add_u32 s55, s55, 0x100
	s_addc_u32 s56, s56, 0
	s_cmp_gt_u32 s57, 13
	s_mov_b64 s[22:23], s[24:25]
	s_cbranch_scc1 .Lpeel_exit_2
.LBB0_409:
	s_add_u32 s24, s22, 0x8000
	s_addc_u32 s25, s23, 0
	s_cmp_eq_u32 s57, 12
	s_cselect_b32 s42, s53, s24
	s_cselect_b32 s43, s11, s25
	s_cselect_b32 s40, s54, s55
	s_cselect_b32 s41, s9, s56
	s_add_u32 s26, s42, 0x4000
	s_addc_u32 s27, s43, 0
	v_add_u32_e32 v145, s76, v142
	s_add_i32 s58, 0, 0x14000
	ds_read_b128 v[146:149], v145
	ds_read_b128 v[150:153], v145 offset:1024
	ds_read_b128 v[160:163], v145 offset:2048
	ds_read_b128 v[164:167], v145 offset:3072
	v_add_u32_e32 v145, s58, v142
	ds_read_b128 v[168:171], v145
	ds_read_b128 v[172:175], v145 offset:1024
	ds_read_b128 v[176:179], v145 offset:2048
	ds_read_b128 v[180:183], v145 offset:3072
	v_lshl_add_u64 v[230:231], s[22:23], 0, v[140:141]
	s_add_i32 m0, s45, 0xc000
	ds_read_b128 v[184:187], v144
	ds_read_b128 v[188:191], v144 offset:1024
	ds_read_b128 v[206:209], v144 offset:2048
	ds_read_b128 v[210:213], v144 offset:3072
	ds_read_b128 v[214:217], v144 offset:4096
	ds_read_b128 v[218:221], v144 offset:5120
	ds_read_b128 v[222:225], v144 offset:6144
	ds_read_b128 v[226:229], v144 offset:7168
	global_load_lds_dwordx4 v[230:231], off
	v_lshl_add_u64 v[230:231], s[22:23], 0, v[138:139]
	s_add_i32 m0, s45, 0xe000
	s_nop 0
	global_load_lds_dwordx4 v[230:231], off
	s_waitcnt vmcnt(8)
	.p2align 3
	s_waitcnt lgkmcnt(0)
	s_barrier
; #define PG8_STAGE(bufoff, gbase, voff) do { _Pragma("unroll") for (int _i = 0; _i < 2; ++_i) \
;         __builtin_amdgcn_global_load_lds((const unsigned*)((const char*)(gbase) + (voff)[_i]), (PG8_LAS unsigned*)(lds + (bufoff) + ldsw + _i * 8192), 16, 0, 0); } while (0)
; #define PG8_LDA(dst, b, h) do { _Pragma("unroll") for (int m = 0; m < 4; ++m) _Pragma("unroll") for (int k = 0; k < 2; ++k) dst[m][k] = *(const PG8_LAS bf16x8*)(lds + PG8_SA(b, h) + aoff + m * 2048 + k * 1024); } while (0)
; #define PG8_MMA(ai, bj, At, Bt) do { __builtin_amdgcn_s_setprio(1); _Pragma("unroll") for (int m = 0; m < 4; ++m) _Pragma("unroll") for (int n = 0; n < 2; ++n) _Pragma("unroll") for (int k = 0; k < 2; ++k) \
;         acc[ai][bj][m][n] = __builtin_amdgcn_mfma_f32_16x16x32_bf16(Bt[n][k], At[m][k], acc[ai][bj][m][n], 0, 0, 0); __builtin_amdgcn_s_setprio(0); } while (0)
; #define PG8_WAIT_V(n) asm volatile("s_waitcnt vmcnt(" #n ")" ::: "memory")
; #define PG8_WAIT_L(n) asm volatile("s_waitcnt lgkmcnt(" #n ")" ::: "memory")
; #define PG8_BAR __builtin_amdgcn_s_barrier()
; #define PG8_SCHED __builtin_amdgcn_sched_barrier(0)
; template <class Epi, class Sched, bool ALIGN_EPI = false, bool SP2 = false>
; __device__ __forceinline__ void gemm_phase(PG8_LAS unsigned char* lds, const Gemm g, const Sched& S, const Epi& E) {
;     ...
;             PG8_WAIT_V(8); PG8_WAIT_L(0); PG8_BAR; PG8_MMA(0, 0, At, B0); PG8_MMA(0, 1, At, B1); PG8_BAR; PG8_SCHED;
;             PG8_LDA(At, 0, 1); PG8_STAGE(PG8_SB(0, 0), b2, voffB); PG8_STAGE(PG8_SB(0, 1), b2 + hstep, voffB); PG8_STAGE(PG8_SA(0, 0), a2, voffA);
;             PG8_WAIT_V(8); PG8_WAIT_L(0); PG8_BAR; PG8_MMA(1, 0, At, B0); PG8_MMA(1, 1, At, B1); PG8_BAR; PG8_SCHED;
	v_mfma_f32_16x16x32_bf16 v[126:129], v[146:149], v[184:187], v[126:129]
	v_mfma_f32_16x16x32_bf16 v[126:129], v[150:153], v[188:191], v[126:129]
	v_mfma_f32_16x16x32_bf16 v[118:121], v[164:167], v[188:191], v[118:121]
	v_mfma_f32_16x16x32_bf16 v[118:121], v[160:163], v[184:187], v[118:121]
	v_mfma_f32_16x16x32_bf16 v[102:105], v[160:163], v[206:209], v[102:105]
	v_mfma_f32_16x16x32_bf16 v[102:105], v[164:167], v[210:213], v[102:105]
	v_mfma_f32_16x16x32_bf16 v[110:113], v[150:153], v[210:213], v[110:113]
	v_mfma_f32_16x16x32_bf16 v[110:113], v[146:149], v[206:209], v[110:113]
	v_mfma_f32_16x16x32_bf16 v[94:97], v[146:149], v[214:217], v[94:97]
	v_mfma_f32_16x16x32_bf16 v[94:97], v[150:153], v[218:221], v[94:97]
	v_mfma_f32_16x16x32_bf16 v[86:89], v[164:167], v[218:221], v[86:89]
	v_mfma_f32_16x16x32_bf16 v[86:89], v[160:163], v[214:217], v[86:89]
	v_mfma_f32_16x16x32_bf16 v[70:73], v[160:163], v[222:225], v[70:73]
	v_mfma_f32_16x16x32_bf16 v[70:73], v[164:167], v[226:229], v[70:73]
	v_mfma_f32_16x16x32_bf16 v[78:81], v[150:153], v[226:229], v[78:81]
	v_mfma_f32_16x16x32_bf16 v[78:81], v[146:149], v[222:225], v[78:81]
	v_mfma_f32_16x16x32_bf16 v[122:125], v[168:171], v[184:187], v[122:125]
	v_mfma_f32_16x16x32_bf16 v[122:125], v[172:175], v[188:191], v[122:125]
	v_mfma_f32_16x16x32_bf16 v[114:117], v[180:183], v[188:191], v[114:117]
	v_mfma_f32_16x16x32_bf16 v[114:117], v[176:179], v[184:187], v[114:117]
	v_mfma_f32_16x16x32_bf16 v[98:101], v[176:179], v[206:209], v[98:101]
	v_mfma_f32_16x16x32_bf16 v[98:101], v[180:183], v[210:213], v[98:101]
	v_mfma_f32_16x16x32_bf16 v[106:109], v[172:175], v[210:213], v[106:109]
	v_mfma_f32_16x16x32_bf16 v[106:109], v[168:171], v[206:209], v[106:109]
	v_mfma_f32_16x16x32_bf16 v[90:93], v[168:171], v[214:217], v[90:93]
	v_mfma_f32_16x16x32_bf16 v[90:93], v[172:175], v[218:221], v[90:93]
	v_mfma_f32_16x16x32_bf16 v[82:85], v[180:183], v[218:221], v[82:85]
	v_mfma_f32_16x16x32_bf16 v[82:85], v[176:179], v[214:217], v[82:85]
	v_mfma_f32_16x16x32_bf16 v[66:69], v[176:179], v[222:225], v[66:69]
	v_mfma_f32_16x16x32_bf16 v[66:69], v[180:183], v[226:229], v[66:69]
	v_mfma_f32_16x16x32_bf16 v[74:77], v[172:175], v[226:229], v[74:77]
	v_mfma_f32_16x16x32_bf16 v[74:77], v[168:171], v[222:225], v[74:77]
	s_barrier
	s_add_i32 s22, s76, s29
	v_lshl_add_u64 v[230:231], s[40:41], 0, v[0:1]
	s_mov_b32 m0, s22
	ds_read_b128 v[184:187], v144 offset:16384
	ds_read_b128 v[188:191], v144 offset:17408
	ds_read_b128 v[206:209], v144 offset:18432
	ds_read_b128 v[210:213], v144 offset:19456
	ds_read_b128 v[214:217], v144 offset:20480
	ds_read_b128 v[218:221], v144 offset:21504
	ds_read_b128 v[222:225], v144 offset:22528
	ds_read_b128 v[226:229], v144 offset:23552
	global_load_lds_dwordx4 v[230:231], off
	s_add_i32 m0, s22, 0x2000
	s_add_u32 s22, s40, 0x40000
	v_lshl_add_u64 v[232:233], s[40:41], 0, v[130:131]
	s_addc_u32 s23, s41, 0
	s_add_i32 s58, s58, s29
	global_load_lds_dwordx4 v[232:233], off
	v_lshl_add_u64 v[234:235], s[22:23], 0, v[0:1]
	s_mov_b32 m0, s58
	s_nop 0
	global_load_lds_dwordx4 v[234:235], off
	v_lshl_add_u64 v[234:235], s[22:23], 0, v[130:131]
	s_add_i32 m0, s58, 0x2000
	s_nop 0
	global_load_lds_dwordx4 v[234:235], off
	v_lshl_add_u64 v[234:235], s[42:43], 0, v[134:135]
	s_mov_b32 m0, s45
	s_nop 0
	global_load_lds_dwordx4 v[234:235], off
	v_lshl_add_u64 v[234:235], s[42:43], 0, v[132:133]
	s_mov_b32 m0, s46
	s_nop 0
	global_load_lds_dwordx4 v[234:235], off
	s_waitcnt vmcnt(8)
	.p2align 3
	s_waitcnt lgkmcnt(0)
	s_barrier
	v_mfma_f32_16x16x32_bf16 v[62:65], v[146:149], v[184:187], v[62:65]
	v_mfma_f32_16x16x32_bf16 v[62:65], v[150:153], v[188:191], v[62:65]
	v_mfma_f32_16x16x32_bf16 v[54:57], v[164:167], v[188:191], v[54:57]
	v_mfma_f32_16x16x32_bf16 v[54:57], v[160:163], v[184:187], v[54:57]
	v_mfma_f32_16x16x32_bf16 v[38:41], v[160:163], v[206:209], v[38:41]
	v_mfma_f32_16x16x32_bf16 v[38:41], v[164:167], v[210:213], v[38:41]
	v_mfma_f32_16x16x32_bf16 v[46:49], v[150:153], v[210:213], v[46:49]
	v_mfma_f32_16x16x32_bf16 v[46:49], v[146:149], v[206:209], v[46:49]
	v_mfma_f32_16x16x32_bf16 v[30:33], v[146:149], v[214:217], v[30:33]
	v_mfma_f32_16x16x32_bf16 v[30:33], v[150:153], v[218:221], v[30:33]
	v_mfma_f32_16x16x32_bf16 v[22:25], v[164:167], v[218:221], v[22:25]
	v_mfma_f32_16x16x32_bf16 v[22:25], v[160:163], v[214:217], v[22:25]
	v_mfma_f32_16x16x32_bf16 v[6:9], v[160:163], v[222:225], v[6:9]
	v_mfma_f32_16x16x32_bf16 v[6:9], v[164:167], v[226:229], v[6:9]
	v_mfma_f32_16x16x32_bf16 v[14:17], v[150:153], v[226:229], v[14:17]
	v_mfma_f32_16x16x32_bf16 v[14:17], v[146:149], v[222:225], v[14:17]
	v_mfma_f32_16x16x32_bf16 v[58:61], v[168:171], v[184:187], v[58:61]
	v_mfma_f32_16x16x32_bf16 v[58:61], v[172:175], v[188:191], v[58:61]
	v_mfma_f32_16x16x32_bf16 v[50:53], v[180:183], v[188:191], v[50:53]
	v_mfma_f32_16x16x32_bf16 v[50:53], v[176:179], v[184:187], v[50:53]
	v_mfma_f32_16x16x32_bf16 v[34:37], v[176:179], v[206:209], v[34:37]
	v_mfma_f32_16x16x32_bf16 v[34:37], v[180:183], v[210:213], v[34:37]
	v_mfma_f32_16x16x32_bf16 v[42:45], v[172:175], v[210:213], v[42:45]
	v_mfma_f32_16x16x32_bf16 v[42:45], v[168:171], v[206:209], v[42:45]
	v_mfma_f32_16x16x32_bf16 v[26:29], v[168:171], v[214:217], v[26:29]
	v_mfma_f32_16x16x32_bf16 v[26:29], v[172:175], v[218:221], v[26:29]
	v_mfma_f32_16x16x32_bf16 v[18:21], v[180:183], v[218:221], v[18:21]
	v_mfma_f32_16x16x32_bf16 v[18:21], v[176:179], v[214:217], v[18:21]
	v_mfma_f32_16x16x32_bf16 v[2:5], v[176:179], v[222:225], v[2:5]
	v_mfma_f32_16x16x32_bf16 v[2:5], v[180:183], v[226:229], v[2:5]
	v_mfma_f32_16x16x32_bf16 v[10:13], v[172:175], v[226:229], v[10:13]
	v_mfma_f32_16x16x32_bf16 v[10:13], v[168:171], v[222:225], v[10:13]
	s_barrier
; #define PG8_STAGE(bufoff, gbase, voff) do { _Pragma("unroll") for (int _i = 0; _i < 2; ++_i) \
;         __builtin_amdgcn_global_load_lds((const unsigned*)((const char*)(gbase) + (voff)[_i]), (PG8_LAS unsigned*)(lds + (bufoff) + ldsw + _i * 8192), 16, 0, 0); } while (0)
; #define PG8_LDA(dst, b, h) do { _Pragma("unroll") for (int m = 0; m < 4; ++m) _Pragma("unroll") for (int k = 0; k < 2; ++k) dst[m][k] = *(const PG8_LAS bf16x8*)(lds + PG8_SA(b, h) + aoff + m * 2048 + k * 1024); } while (0)
; #define PG8_LDB(dst, b, h) do { _Pragma("unroll") for (int n = 0; n < 2; ++n) _Pragma("unroll") for (int k = 0; k < 2; ++k) dst[n][k] = *(const PG8_LAS bf16x8*)(lds + PG8_SB(b, h) + boff + n * 2048 + k * 1024); } while (0)
; #define PG8_MMA(ai, bj, At, Bt) do { __builtin_amdgcn_s_setprio(1); _Pragma("unroll") for (int m = 0; m < 4; ++m) _Pragma("unroll") for (int n = 0; n < 2; ++n) _Pragma("unroll") for (int k = 0; k < 2; ++k) \
;         acc[ai][bj][m][n] = __builtin_amdgcn_mfma_f32_16x16x32_bf16(Bt[n][k], At[m][k], acc[ai][bj][m][n], 0, 0, 0); __builtin_amdgcn_s_setprio(0); } while (0)
; #define PG8_WAIT_V(n) asm volatile("s_waitcnt vmcnt(" #n ")" ::: "memory")
; #define PG8_WAIT_L(n) asm volatile("s_waitcnt lgkmcnt(" #n ")" ::: "memory")
; #define PG8_BAR __builtin_amdgcn_s_barrier()
; #define PG8_SCHED __builtin_amdgcn_sched_barrier(0)
; template <class Epi, class Sched, bool ALIGN_EPI = false, bool SP2 = false>
; __device__ __forceinline__ void gemm_phase(PG8_LAS unsigned char* lds, const Gemm g, const Sched& S, const Epi& E) {
;     ...
;             PG8_LDB(B0, 1, 0); PG8_LDB(B1, 1, 1); PG8_SCHED; PG8_LDA(At, 1, 0); PG8_STAGE(PG8_SA(0, 1), a2 + hstep, voffA);
;             PG8_WAIT_V(8); PG8_WAIT_L(0); PG8_BAR; PG8_MMA(0, 0, At, B0); PG8_MMA(0, 1, At, B1); PG8_BAR; PG8_SCHED;
;             PG8_LDA(At, 1, 1); PG8_STAGE(PG8_SB(1, 0), b3, voffB); PG8_STAGE(PG8_SB(1, 1), b3 + hstep, voffB); PG8_STAGE(PG8_SA(1, 0), a3, voffA);
;             PG8_WAIT_V(8); PG8_WAIT_L(0); PG8_BAR; PG8_MMA(1, 0, At, B0); PG8_MMA(1, 1, At, B1); PG8_BAR; PG8_SCHED;
	s_add_i32 s58, 0, 0x18000
	v_add_u32_e32 v145, s58, v142
	s_add_i32 s59, 0, 0x1c000
	ds_read_b128 v[146:149], v145
	ds_read_b128 v[150:153], v145 offset:1024
	ds_read_b128 v[160:163], v145 offset:2048
	ds_read_b128 v[164:167], v145 offset:3072
	v_add_u32_e32 v145, s59, v142
	ds_read_b128 v[168:171], v145
	ds_read_b128 v[172:175], v145 offset:1024
	ds_read_b128 v[176:179], v145 offset:2048
	ds_read_b128 v[180:183], v145 offset:3072
	s_add_u32 s22, s42, 0x40000
	s_addc_u32 s23, s43, 0
	s_mov_b32 m0, s47
	v_lshl_add_u64 v[234:235], s[22:23], 0, v[134:135]
	ds_read_b128 v[184:187], v144 offset:32768
	ds_read_b128 v[188:191], v144 offset:33792
	ds_read_b128 v[206:209], v144 offset:34816
	ds_read_b128 v[210:213], v144 offset:35840
	ds_read_b128 v[214:217], v144 offset:36864
	ds_read_b128 v[218:221], v144 offset:37888
	ds_read_b128 v[222:225], v144 offset:38912
	ds_read_b128 v[226:229], v144 offset:39936
	global_load_lds_dwordx4 v[234:235], off
	v_lshl_add_u64 v[234:235], s[22:23], 0, v[132:133]
	s_mov_b32 m0, s48
	s_nop 0
	global_load_lds_dwordx4 v[234:235], off
	s_waitcnt vmcnt(8)
	.p2align 3
	s_waitcnt lgkmcnt(0)
	s_barrier
	v_mfma_f32_16x16x32_bf16 v[126:129], v[146:149], v[184:187], v[126:129]
	v_mfma_f32_16x16x32_bf16 v[126:129], v[150:153], v[188:191], v[126:129]
	v_mfma_f32_16x16x32_bf16 v[118:121], v[164:167], v[188:191], v[118:121]
	v_mfma_f32_16x16x32_bf16 v[118:121], v[160:163], v[184:187], v[118:121]
	v_mfma_f32_16x16x32_bf16 v[102:105], v[160:163], v[206:209], v[102:105]
	v_mfma_f32_16x16x32_bf16 v[102:105], v[164:167], v[210:213], v[102:105]
	v_mfma_f32_16x16x32_bf16 v[110:113], v[150:153], v[210:213], v[110:113]
	v_mfma_f32_16x16x32_bf16 v[110:113], v[146:149], v[206:209], v[110:113]
	v_mfma_f32_16x16x32_bf16 v[94:97], v[146:149], v[214:217], v[94:97]
	v_mfma_f32_16x16x32_bf16 v[94:97], v[150:153], v[218:221], v[94:97]
	v_mfma_f32_16x16x32_bf16 v[86:89], v[164:167], v[218:221], v[86:89]
	v_mfma_f32_16x16x32_bf16 v[86:89], v[160:163], v[214:217], v[86:89]
	v_mfma_f32_16x16x32_bf16 v[70:73], v[160:163], v[222:225], v[70:73]
	v_mfma_f32_16x16x32_bf16 v[70:73], v[164:167], v[226:229], v[70:73]
	v_mfma_f32_16x16x32_bf16 v[78:81], v[150:153], v[226:229], v[78:81]
	v_mfma_f32_16x16x32_bf16 v[78:81], v[146:149], v[222:225], v[78:81]
	v_mfma_f32_16x16x32_bf16 v[122:125], v[168:171], v[184:187], v[122:125]
	v_mfma_f32_16x16x32_bf16 v[122:125], v[172:175], v[188:191], v[122:125]
	v_mfma_f32_16x16x32_bf16 v[114:117], v[180:183], v[188:191], v[114:117]
	v_mfma_f32_16x16x32_bf16 v[114:117], v[176:179], v[184:187], v[114:117]
	v_mfma_f32_16x16x32_bf16 v[98:101], v[176:179], v[206:209], v[98:101]
	v_mfma_f32_16x16x32_bf16 v[98:101], v[180:183], v[210:213], v[98:101]
	v_mfma_f32_16x16x32_bf16 v[106:109], v[172:175], v[210:213], v[106:109]
	v_mfma_f32_16x16x32_bf16 v[106:109], v[168:171], v[206:209], v[106:109]
	v_mfma_f32_16x16x32_bf16 v[90:93], v[168:171], v[214:217], v[90:93]
	v_mfma_f32_16x16x32_bf16 v[90:93], v[172:175], v[218:221], v[90:93]
	v_mfma_f32_16x16x32_bf16 v[82:85], v[180:183], v[218:221], v[82:85]
	v_mfma_f32_16x16x32_bf16 v[82:85], v[176:179], v[214:217], v[82:85]
	v_mfma_f32_16x16x32_bf16 v[66:69], v[176:179], v[222:225], v[66:69]
	v_mfma_f32_16x16x32_bf16 v[66:69], v[180:183], v[226:229], v[66:69]
	v_mfma_f32_16x16x32_bf16 v[74:77], v[172:175], v[226:229], v[74:77]
	v_mfma_f32_16x16x32_bf16 v[74:77], v[168:171], v[222:225], v[74:77]
	s_barrier
	s_add_i32 s22, s58, s29
	v_lshl_add_u64 v[230:231], v[230:231], 0, s[38:39]
	s_mov_b32 m0, s22
	ds_read_b128 v[184:187], v144 offset:49152
	ds_read_b128 v[188:191], v144 offset:50176
	ds_read_b128 v[206:209], v144 offset:51200
	ds_read_b128 v[210:213], v144 offset:52224
	ds_read_b128 v[214:217], v144 offset:53248
	ds_read_b128 v[218:221], v144 offset:54272
	ds_read_b128 v[222:225], v144 offset:55296
	ds_read_b128 v[226:229], v144 offset:56320
	global_load_lds_dwordx4 v[230:231], off
	s_add_i32 m0, s22, 0x2000
	s_add_u32 s22, s40, 0x40080
	v_lshl_add_u64 v[230:231], v[232:233], 0, s[38:39]
	s_addc_u32 s23, s41, 0
	s_add_i32 s40, s59, s29
	global_load_lds_dwordx4 v[230:231], off
	v_lshl_add_u64 v[230:231], s[22:23], 0, v[0:1]
	s_mov_b32 m0, s40
	s_nop 0
	global_load_lds_dwordx4 v[230:231], off
	v_lshl_add_u64 v[230:231], s[22:23], 0, v[130:131]
	s_add_i32 m0, s40, 0x2000
	s_nop 0
	global_load_lds_dwordx4 v[230:231], off
	v_lshl_add_u64 v[230:231], s[26:27], 0, v[134:135]
	s_mov_b32 m0, s49
	s_nop 0
	global_load_lds_dwordx4 v[230:231], off
	v_lshl_add_u64 v[230:231], s[26:27], 0, v[132:133]
	s_mov_b32 m0, s50
	s_nop 0
	global_load_lds_dwordx4 v[230:231], off
	s_waitcnt vmcnt(8)
	.p2align 3
	s_waitcnt lgkmcnt(0)
	s_barrier
	v_mfma_f32_16x16x32_bf16 v[62:65], v[146:149], v[184:187], v[62:65]
	v_mfma_f32_16x16x32_bf16 v[62:65], v[150:153], v[188:191], v[62:65]
	v_mfma_f32_16x16x32_bf16 v[54:57], v[164:167], v[188:191], v[54:57]
	v_mfma_f32_16x16x32_bf16 v[54:57], v[160:163], v[184:187], v[54:57]
	v_mfma_f32_16x16x32_bf16 v[38:41], v[160:163], v[206:209], v[38:41]
	v_mfma_f32_16x16x32_bf16 v[38:41], v[164:167], v[210:213], v[38:41]
	v_mfma_f32_16x16x32_bf16 v[46:49], v[150:153], v[210:213], v[46:49]
	v_mfma_f32_16x16x32_bf16 v[46:49], v[146:149], v[206:209], v[46:49]
	v_mfma_f32_16x16x32_bf16 v[30:33], v[146:149], v[214:217], v[30:33]
	v_mfma_f32_16x16x32_bf16 v[30:33], v[150:153], v[218:221], v[30:33]
	v_mfma_f32_16x16x32_bf16 v[22:25], v[164:167], v[218:221], v[22:25]
	v_mfma_f32_16x16x32_bf16 v[22:25], v[160:163], v[214:217], v[22:25]
	v_mfma_f32_16x16x32_bf16 v[6:9], v[160:163], v[222:225], v[6:9]
	v_mfma_f32_16x16x32_bf16 v[6:9], v[164:167], v[226:229], v[6:9]
	v_mfma_f32_16x16x32_bf16 v[14:17], v[150:153], v[226:229], v[14:17]
	v_mfma_f32_16x16x32_bf16 v[14:17], v[146:149], v[222:225], v[14:17]
	v_mfma_f32_16x16x32_bf16 v[58:61], v[168:171], v[184:187], v[58:61]
	v_mfma_f32_16x16x32_bf16 v[58:61], v[172:175], v[188:191], v[58:61]
	v_mfma_f32_16x16x32_bf16 v[50:53], v[180:183], v[188:191], v[50:53]
	v_mfma_f32_16x16x32_bf16 v[50:53], v[176:179], v[184:187], v[50:53]
	v_mfma_f32_16x16x32_bf16 v[34:37], v[176:179], v[206:209], v[34:37]
	v_mfma_f32_16x16x32_bf16 v[34:37], v[180:183], v[210:213], v[34:37]
	v_mfma_f32_16x16x32_bf16 v[42:45], v[172:175], v[210:213], v[42:45]
	v_mfma_f32_16x16x32_bf16 v[42:45], v[168:171], v[206:209], v[42:45]
	v_mfma_f32_16x16x32_bf16 v[26:29], v[168:171], v[214:217], v[26:29]
	v_mfma_f32_16x16x32_bf16 v[26:29], v[172:175], v[218:221], v[26:29]
	v_mfma_f32_16x16x32_bf16 v[18:21], v[180:183], v[218:221], v[18:21]
	v_mfma_f32_16x16x32_bf16 v[18:21], v[176:179], v[214:217], v[18:21]
	v_mfma_f32_16x16x32_bf16 v[2:5], v[176:179], v[222:225], v[2:5]
	v_mfma_f32_16x16x32_bf16 v[2:5], v[180:183], v[226:229], v[2:5]
	v_mfma_f32_16x16x32_bf16 v[10:13], v[172:175], v[226:229], v[10:13]
	v_mfma_f32_16x16x32_bf16 v[10:13], v[168:171], v[222:225], v[10:13]
	s_barrier
	s_add_i32 s57, s57, 2
	s_add_u32 s55, s55, 0x100
	s_addc_u32 s56, s56, 0
	s_cmp_gt_u32 s57, 13
	s_mov_b64 s[22:23], s[24:25]
	s_cbranch_scc0 .LBB0_409
